# final rmsnorm fused into the last down-GEMM epilogue via 4-owner row-panel exchange; residual stream of P7 moved to d_ws; P10 and its grid barrier removed
# speedup vs baseline: 1.0082x; 1.0067x over previous
; #define PG8_STAGE(bufoff, gbase, voff) do { _Pragma("unroll") for (int _i = 0; _i < 2; ++_i) \
;         __builtin_amdgcn_global_load_lds((const unsigned*)((const char*)(gbase) + (voff)[_i]), (PG8_LAS unsigned*)(lds + (bufoff) + ldsw + _i * 8192), 16, 0, 0); } while (0)
; #define PG8_WAIT_V(n) asm volatile("s_waitcnt vmcnt(" #n ")" ::: "memory")
; #define PG8_BAR __builtin_amdgcn_s_barrier()
; template <class Epi, class Sched, bool ALIGN_EPI = false, bool SP2 = false>
; __device__ __forceinline__ void gemm_phase(PG8_LAS unsigned char* lds, const Gemm g, const Sched& S, const Epi& E) {
;     ...
;     for (int i = 0; i < 2; ++i) { int R, C; stage_rc(tid * 16 + i * 8192, R, C); const int Rb = Epi::PERM ? ((R & ~31) + perm32(R & 31)) : R;
;         voffA[i] = Epi::AIL ? (unsigned)((R >> 1) * (2 * K) + (C >> 5) * 64 + (R & 1) * 32 + (C & 31)) * 2u : (unsigned)(R * K + C) * 2u; voffB[i] = (unsigned)(Rb * K + C) * 2u; }
;     const size_t kstep = (size_t)(BK * 2);
;     const size_t kstepA = Epi::AIL ? (size_t)(BK * 4) : kstep;
;     const size_t hstep = (size_t)HALF * K * 2;
;     const size_t tstep = 2 * hstep;
;     const unsigned ldsw = (unsigned)wid * 1024u;
;     const int aoff = lds_byte(wr * 64 + fr, fq * 8), boff = lds_byte(wc * 32 + fr, fq * 8);
;     ...
;     const char* cA = PG8_ABASE(cur); const char* cB = PG8_BBASE(cur);
;     S.a_ready(cur);
;     if constexpr (SP2) {
;         PG8_STAGE(PG8_SB(0, 0), cB, voffB); PG8_STAGE(PG8_SB(0, 1), cB + hstep, voffB); PG8_STAGE(PG8_SA(0, 0), cA, voffA); PG8_STAGE(PG8_SA(0, 1), cA + hstep, voffA);
;         if (wr == 1) PG8_BAR;
;         PG8_WAIT_V(2); PG8_BAR;
;         PG8_STAGE(PG8_SB(1, 0), cB + kstep, voffB); PG8_STAGE(PG8_SA(1, 0), cA + kstepA, voffA); PG8_STAGE(PG8_SB(1, 1), cB + hstep + kstep, voffB);
;         PG8_WAIT_V(6); PG8_BAR;
.LBB0_825:
	v_readlane_b32 s4, v254, 1
	v_readlane_b32 s5, v254, 2
	s_load_dwordx2 s[10:11], s[4:5], 0x70
	s_andn2_b64 vcc, exec, s[2:3]
	s_cbranch_vccnz .LBB0_925
	v_lshrrev_b32_e32 v3, 1, v0
	v_lshrrev_b32_e32 v4, 5, v0
	v_lshlrev_b32_e32 v1, 4, v0
	v_and_b32_e32 v2, 32, v0
	v_and_b32_e32 v3, 24, v3
	v_and_b32_e32 v4, 4, v4
	v_bfe_u32 v5, v0, 2, 2
	s_add_u32 s100, s78, 0x18000000
	s_addc_u32 s101, s79, 0
	s_add_u32 s46, s78, 0x4000000
	v_bfe_u32 v12, v0, 2, 4
	v_bitop3_b32 v10, v1, v2, 48 bitop3:0x6c
	v_and_b32_e32 v11, 64, v0
	v_or3_b32 v3, v4, v5, v3
	v_lshrrev_b32_e32 v4, 3, v0
	v_or_b32_e32 v13, 0x2000, v1
	s_addc_u32 s47, s79, 0
	v_or_b32_e32 v2, v10, v11
	v_and_or_b32 v5, v4, 48, v12
	v_and_or_b32 v4, v4, 32, v3
	v_lshrrev_b32_e32 v1, 7, v13
	s_movk_i32 s1, 0x70
	s_add_u32 s48, s78, 0x2b00000
	v_lshl_or_b32 v156, v4, 11, v2
	v_and_or_b32 v4, v1, s1, v12
	s_movk_i32 s1, 0x60
	s_addc_u32 s49, s79, 0
	s_lshr_b32 s3, s22, 6
	v_and_or_b32 v1, v1, s1, v3
	s_ashr_i32 s1, s0, 31
	s_ashr_i32 s15, s14, 31
	s_lshr_b32 s2, s22, 8
	s_lshl_b32 s50, s3, 10
	s_lshl_b64 s[4:5], s[0:1], 19
	s_lshl_b64 s[6:7], s[14:15], 19
	s_add_u32 s6, s48, s6
	s_addc_u32 s7, s49, s7
	s_add_i32 s51, s50, 0
	s_add_i32 m0, s51, 0x10000
	v_lshl_or_b32 v160, v1, 11, v2
	global_load_lds_dwordx4 v156, s[6:7]
	s_add_i32 m0, s51, 0x12000
	s_add_u32 s16, s6, 0x40000
	global_load_lds_dwordx4 v160, s[6:7]
	s_addc_u32 s17, s7, 0
	s_add_i32 m0, s51, 0x14000
	v_lshl_or_b32 v154, v5, 11, v2
	global_load_lds_dwordx4 v156, s[16:17]
	s_add_i32 m0, s51, 0x16000
	s_add_u32 s4, s46, s4
	s_addc_u32 s5, s47, s5
	s_add_i32 s52, s51, 0x2000
	global_load_lds_dwordx4 v160, s[16:17]
	s_mov_b32 m0, s51
	s_add_u32 s16, s4, 0x40000
	v_lshl_or_b32 v158, v4, 11, v2
	global_load_lds_dwordx4 v154, s[4:5]
	s_mov_b32 m0, s52
	s_addc_u32 s17, s5, 0
	s_add_i32 s53, s51, 0x4000
	global_load_lds_dwordx4 v158, s[4:5]
	s_mov_b32 m0, s53
	s_add_i32 s54, s51, 0x6000
	global_load_lds_dwordx4 v154, s[16:17]
	s_mov_b32 m0, s54
	v_mov_b32_e32 v163, 0
	global_load_lds_dwordx4 v158, s[16:17]
	v_mov_b32_e32 v157, v163
	v_mov_b32_e32 v161, v163
	v_mov_b32_e32 v155, v163
	v_mov_b32_e32 v159, v163
	s_cmp_eq_u32 s2, 1
	s_mov_b32 s15, 0
	v_lshl_add_u64 v[8:9], s[6:7], 0, v[156:157]
	v_lshl_add_u64 v[6:7], s[6:7], 0, v[160:161]
	v_lshl_add_u64 v[2:3], s[4:5], 0, v[154:155]
	s_cselect_b64 s[16:17], -1, 0
	s_cmp_lg_u32 s2, 1
	v_lshl_add_u64 v[4:5], s[4:5], 0, v[158:159]
	s_cbranch_scc1 .LBB0_828
	s_barrier

; #define PG8_LAS __attribute__((address_space(3)))
; __device__ __forceinline__ void store_lines(PG8_LAS unsigned char* stg, const u32x4 P0, const u32x4 P1, int fr, int fq, bf16_t* seg0, int pitch) {
;     const int ln = fq * 16 + fr;
; #pragma unroll
;     for (int h = 0; h < 2; ++h) {
;         if ((fr >> 3) == h) { *(PG8_LAS u32x4*)(stg + (fr & 7) * 128 + fq * 16) = P0; *(PG8_LAS u32x4*)(stg + (fr & 7) * 128 + 64 + fq * 16) = P1; }
;         __builtin_amdgcn_wave_barrier(); asm volatile("" ::: "memory");
;         const u32x4 v = *(const PG8_LAS u32x4*)(stg + ln * 16);
;         __builtin_amdgcn_wave_barrier(); asm volatile("" ::: "memory");
;         *(u32x4*)(seg0 + (size_t)(8 * h + (ln >> 3)) * pitch + (ln & 7) * 8) = v; }
;     __device__ __forceinline__ void operator()(const f32x4 (&acc)[2][2][4][2], const Unit& u, int wr, int wc, int fr, int fq) const {
;     ...
;             { const size_t seg = (size_t)(row - fr) * DM + u.pn * BM + wc * 64;
;               store_lines(st, pn_[0], pn_[1], fr, fq, xnew + seg, DM);
;               if (XS) store_lines(st, ps_[0], ps_[1], fr, fq, xs + seg, DM); }
.LBB0_843:
	s_or_b64 exec, exec, s[0:1]
	s_ashr_i32 s5, s4, 31
	s_ashr_i32 s41, s40, 31
	s_or_b64 s[36:37], s[4:5], s[24:25]
	v_add_u32_e32 v162, v162, v218
	s_lshl_b64 s[0:1], s[40:41], 10
	v_lshlrev_b32_e32 v210, 4, v162
	s_add_u32 s0, s0, s36
	s_addc_u32 s1, s1, s37
	v_add_u32_e32 v219, s67, v210
	v_ashrrev_i32_e32 v208, 3, v162
	v_lshlrev_b32_e32 v162, 3, v218
	s_lshl_b64 s[0:1], s[0:1], 1
	ds_read_b128 v[224:227], v219
	v_and_b32_e32 v162, 56, v162
	s_add_u32 s6, s100, s0
	v_ashrrev_i32_e32 v209, 31, v208
	v_and_b32_e32 v211, -8, v218
	s_addc_u32 s7, s101, s1
	v_lshlrev_b32_e32 v162, 1, v162
	v_cmp_eq_u32_e64 s[4:5], 8, v211
	v_lshl_add_u64 v[210:211], s[6:7], 0, v[162:163]
	v_lshlrev_b64 v[228:229], 11, v[208:209]
	v_lshl_add_u64 v[228:229], v[210:211], 0, v[228:229]
	s_waitcnt lgkmcnt(0)
	global_store_dwordx4 v[228:229], v[224:227], off
	s_and_saveexec_b64 s[6:7], s[4:5]
	s_cbranch_execz .LBB0_845
	ds_write_b128 v221, v[142:145]
	ds_write_b128 v221, v[134:137] offset:64

; #define PG8_LAS __attribute__((address_space(3)))
; __device__ __forceinline__ void store_lines(PG8_LAS unsigned char* stg, const u32x4 P0, const u32x4 P1, int fr, int fq, bf16_t* seg0, int pitch) {
;     const int ln = fq * 16 + fr;
; #pragma unroll
;     for (int h = 0; h < 2; ++h) {
;         if ((fr >> 3) == h) { *(PG8_LAS u32x4*)(stg + (fr & 7) * 128 + fq * 16) = P0; *(PG8_LAS u32x4*)(stg + (fr & 7) * 128 + 64 + fq * 16) = P1; }
;         __builtin_amdgcn_wave_barrier(); asm volatile("" ::: "memory");
;         const u32x4 v = *(const PG8_LAS u32x4*)(stg + ln * 16);
;         __builtin_amdgcn_wave_barrier(); asm volatile("" ::: "memory");
;         *(u32x4*)(seg0 + (size_t)(8 * h + (ln >> 3)) * pitch + (ln & 7) * 8) = v; }
;     __device__ __forceinline__ void operator()(const f32x4 (&acc)[2][2][4][2], const Unit& u, int wr, int wc, int fr, int fq) const {
;     ...
;             { const size_t seg = (size_t)(row - fr) * DM + u.pn * BM + wc * 64;
;               store_lines(st, pn_[0], pn_[1], fr, fq, xnew + seg, DM);
;               if (XS) store_lines(st, ps_[0], ps_[1], fr, fq, xs + seg, DM); }
.LBB0_853:
	s_or_b64 exec, exec, s[0:1]
	s_or_b32 s0, s40, 16
	s_ashr_i32 s1, s0, 31
	s_lshl_b64 s[42:43], s[0:1], 10
	s_add_u32 s42, s42, s36
	s_addc_u32 s43, s43, s37
	s_lshl_b64 s[42:43], s[42:43], 1
	ds_read_b128 v[200:203], v219
	s_add_u32 s44, s100, s42
	s_addc_u32 s45, s101, s43
	v_lshl_add_u64 v[196:197], s[44:45], 0, v[162:163]
	v_lshl_add_u64 v[204:205], v[142:143], 1, v[196:197]
	s_waitcnt lgkmcnt(0)
	global_store_dwordx4 v[204:205], v[200:203], off
	s_and_saveexec_b64 s[44:45], s[4:5]
	s_cbranch_execz .LBB0_855
	ds_write_b128 v221, v[126:129]
	ds_write_b128 v221, v[118:121] offset:64

; #define PG8_LAS __attribute__((address_space(3)))
; __device__ __forceinline__ void store_lines(PG8_LAS unsigned char* stg, const u32x4 P0, const u32x4 P1, int fr, int fq, bf16_t* seg0, int pitch) {
;     const int ln = fq * 16 + fr;
; #pragma unroll
;     for (int h = 0; h < 2; ++h) {
;         if ((fr >> 3) == h) { *(PG8_LAS u32x4*)(stg + (fr & 7) * 128 + fq * 16) = P0; *(PG8_LAS u32x4*)(stg + (fr & 7) * 128 + 64 + fq * 16) = P1; }
;         __builtin_amdgcn_wave_barrier(); asm volatile("" ::: "memory");
;         const u32x4 v = *(const PG8_LAS u32x4*)(stg + ln * 16);
;         __builtin_amdgcn_wave_barrier(); asm volatile("" ::: "memory");
;         *(u32x4*)(seg0 + (size_t)(8 * h + (ln >> 3)) * pitch + (ln & 7) * 8) = v; }
;     __device__ __forceinline__ void operator()(const f32x4 (&acc)[2][2][4][2], const Unit& u, int wr, int wc, int fr, int fq) const {
;     ...
;             { const size_t seg = (size_t)(row - fr) * DM + u.pn * BM + wc * 64;
;               store_lines(st, pn_[0], pn_[1], fr, fq, xnew + seg, DM);
;               if (XS) store_lines(st, ps_[0], ps_[1], fr, fq, xs + seg, DM); }
.LBB0_863:
	s_or_b64 exec, exec, s[0:1]
	s_or_b32 s0, s40, 32
	s_ashr_i32 s1, s0, 31
	s_lshl_b64 s[42:43], s[0:1], 10
	s_add_u32 s42, s42, s36
	s_addc_u32 s43, s43, s37
	s_lshl_b64 s[42:43], s[42:43], 1
	ds_read_b128 v[144:147], v219
	s_add_u32 s44, s100, s42
	s_addc_u32 s45, s101, s43
	v_lshl_add_u64 v[140:141], s[44:45], 0, v[162:163]
	v_lshl_add_u64 v[148:149], v[142:143], 1, v[140:141]
	s_waitcnt lgkmcnt(0)
	global_store_dwordx4 v[148:149], v[144:147], off
	s_and_saveexec_b64 s[44:45], s[4:5]
	s_cbranch_execz .LBB0_865
	ds_write_b128 v221, v[110:113]
	ds_write_b128 v221, v[102:105] offset:64

; #define PG8_LAS __attribute__((address_space(3)))
; __device__ __forceinline__ void store_lines(PG8_LAS unsigned char* stg, const u32x4 P0, const u32x4 P1, int fr, int fq, bf16_t* seg0, int pitch) {
;     const int ln = fq * 16 + fr;
; #pragma unroll
;     for (int h = 0; h < 2; ++h) {
;         if ((fr >> 3) == h) { *(PG8_LAS u32x4*)(stg + (fr & 7) * 128 + fq * 16) = P0; *(PG8_LAS u32x4*)(stg + (fr & 7) * 128 + 64 + fq * 16) = P1; }
;         __builtin_amdgcn_wave_barrier(); asm volatile("" ::: "memory");
;         const u32x4 v = *(const PG8_LAS u32x4*)(stg + ln * 16);
;         __builtin_amdgcn_wave_barrier(); asm volatile("" ::: "memory");
;         *(u32x4*)(seg0 + (size_t)(8 * h + (ln >> 3)) * pitch + (ln & 7) * 8) = v; }
;     __device__ __forceinline__ void operator()(const f32x4 (&acc)[2][2][4][2], const Unit& u, int wr, int wc, int fr, int fq) const {
;     ...
;             { const size_t seg = (size_t)(row - fr) * DM + u.pn * BM + wc * 64;
;               store_lines(st, pn_[0], pn_[1], fr, fq, xnew + seg, DM);
;               if (XS) store_lines(st, ps_[0], ps_[1], fr, fq, xs + seg, DM); }
.LBB0_873:
	s_or_b64 exec, exec, s[0:1]
	s_or_b32 s0, s40, 48
	s_ashr_i32 s1, s0, 31
	s_lshl_b64 s[42:43], s[0:1], 10
	s_add_u32 s42, s42, s36
	s_addc_u32 s43, s43, s37
	s_lshl_b64 s[42:43], s[42:43], 1
	ds_read_b128 v[124:127], v219
	s_add_u32 s44, s100, s42
	s_addc_u32 s45, s101, s43
	v_lshl_add_u64 v[122:123], s[44:45], 0, v[162:163]
	v_lshl_add_u64 v[128:129], v[142:143], 1, v[122:123]
	s_waitcnt lgkmcnt(0)
	global_store_dwordx4 v[128:129], v[124:127], off
	s_and_saveexec_b64 s[44:45], s[4:5]
	s_cbranch_execz .LBB0_875
	ds_write_b128 v221, v[94:97]
	ds_write_b128 v221, v[86:89] offset:64

; #define PG8_LAS __attribute__((address_space(3)))
; __device__ __forceinline__ void store_lines(PG8_LAS unsigned char* stg, const u32x4 P0, const u32x4 P1, int fr, int fq, bf16_t* seg0, int pitch) {
;     const int ln = fq * 16 + fr;
; #pragma unroll
;     for (int h = 0; h < 2; ++h) {
;         if ((fr >> 3) == h) { *(PG8_LAS u32x4*)(stg + (fr & 7) * 128 + fq * 16) = P0; *(PG8_LAS u32x4*)(stg + (fr & 7) * 128 + 64 + fq * 16) = P1; }
;         __builtin_amdgcn_wave_barrier(); asm volatile("" ::: "memory");
;         const u32x4 v = *(const PG8_LAS u32x4*)(stg + ln * 16);
;         __builtin_amdgcn_wave_barrier(); asm volatile("" ::: "memory");
;         *(u32x4*)(seg0 + (size_t)(8 * h + (ln >> 3)) * pitch + (ln & 7) * 8) = v; }
;     __device__ __forceinline__ void operator()(const f32x4 (&acc)[2][2][4][2], const Unit& u, int wr, int wc, int fr, int fq) const {
;     ...
;             { const size_t seg = (size_t)(row - fr) * DM + u.pn * BM + wc * 64;
;               store_lines(st, pn_[0], pn_[1], fr, fq, xnew + seg, DM);
;               if (XS) store_lines(st, ps_[0], ps_[1], fr, fq, xs + seg, DM); }
.LBB0_883:
	s_or_b64 exec, exec, s[0:1]
	s_add_i32 s0, s40, 0x80
	s_ashr_i32 s1, s0, 31
	s_lshl_b64 s[40:41], s[0:1], 10
	s_add_u32 s40, s40, s36
	s_addc_u32 s41, s41, s37
	s_lshl_b64 s[40:41], s[40:41], 1
	ds_read_b128 v[108:111], v219
	s_add_u32 s42, s100, s40
	s_addc_u32 s43, s101, s41
	v_lshl_add_u64 v[106:107], s[42:43], 0, v[162:163]
	v_lshl_add_u64 v[112:113], v[142:143], 1, v[106:107]
	s_waitcnt lgkmcnt(0)
	global_store_dwordx4 v[112:113], v[108:111], off
	s_and_saveexec_b64 s[42:43], s[4:5]
	s_cbranch_execz .LBB0_885
	ds_write_b128 v221, v[78:81]
	ds_write_b128 v221, v[62:65] offset:64

; #define PG8_LAS __attribute__((address_space(3)))
; __device__ __forceinline__ void store_lines(PG8_LAS unsigned char* stg, const u32x4 P0, const u32x4 P1, int fr, int fq, bf16_t* seg0, int pitch) {
;     const int ln = fq * 16 + fr;
; #pragma unroll
;     for (int h = 0; h < 2; ++h) {
;         if ((fr >> 3) == h) { *(PG8_LAS u32x4*)(stg + (fr & 7) * 128 + fq * 16) = P0; *(PG8_LAS u32x4*)(stg + (fr & 7) * 128 + 64 + fq * 16) = P1; }
;         __builtin_amdgcn_wave_barrier(); asm volatile("" ::: "memory");
;         const u32x4 v = *(const PG8_LAS u32x4*)(stg + ln * 16);
;         __builtin_amdgcn_wave_barrier(); asm volatile("" ::: "memory");
;         *(u32x4*)(seg0 + (size_t)(8 * h + (ln >> 3)) * pitch + (ln & 7) * 8) = v; }
;     __device__ __forceinline__ void operator()(const f32x4 (&acc)[2][2][4][2], const Unit& u, int wr, int wc, int fr, int fq) const {
;     ...
;             { const size_t seg = (size_t)(row - fr) * DM + u.pn * BM + wc * 64;
;               store_lines(st, pn_[0], pn_[1], fr, fq, xnew + seg, DM);
;               if (XS) store_lines(st, ps_[0], ps_[1], fr, fq, xs + seg, DM); }
.LBB0_893:
	s_or_b64 exec, exec, s[40:41]
	s_or_b32 s40, s0, 16
	s_ashr_i32 s41, s40, 31
	s_lshl_b64 s[42:43], s[40:41], 10
	s_add_u32 s42, s42, s36
	s_addc_u32 s43, s43, s37
	s_lshl_b64 s[42:43], s[42:43], 1
	ds_read_b128 v[92:95], v219
	s_add_u32 s44, s100, s42
	s_addc_u32 s45, s101, s43
	v_lshl_add_u64 v[90:91], s[44:45], 0, v[162:163]
	v_lshl_add_u64 v[96:97], v[142:143], 1, v[90:91]
	s_waitcnt lgkmcnt(0)
	global_store_dwordx4 v[96:97], v[92:95], off
	s_and_saveexec_b64 s[44:45], s[4:5]
	s_cbranch_execz .LBB0_895
	ds_write_b128 v221, v[46:49]
	ds_write_b128 v221, v[38:41] offset:64

; #define PG8_LAS __attribute__((address_space(3)))
; __device__ __forceinline__ void store_lines(PG8_LAS unsigned char* stg, const u32x4 P0, const u32x4 P1, int fr, int fq, bf16_t* seg0, int pitch) {
;     const int ln = fq * 16 + fr;
; #pragma unroll
;     for (int h = 0; h < 2; ++h) {
;         if ((fr >> 3) == h) { *(PG8_LAS u32x4*)(stg + (fr & 7) * 128 + fq * 16) = P0; *(PG8_LAS u32x4*)(stg + (fr & 7) * 128 + 64 + fq * 16) = P1; }
;         __builtin_amdgcn_wave_barrier(); asm volatile("" ::: "memory");
;         const u32x4 v = *(const PG8_LAS u32x4*)(stg + ln * 16);
;         __builtin_amdgcn_wave_barrier(); asm volatile("" ::: "memory");
;         *(u32x4*)(seg0 + (size_t)(8 * h + (ln >> 3)) * pitch + (ln & 7) * 8) = v; }
;     __device__ __forceinline__ void operator()(const f32x4 (&acc)[2][2][4][2], const Unit& u, int wr, int wc, int fr, int fq) const {
;     ...
;             { const size_t seg = (size_t)(row - fr) * DM + u.pn * BM + wc * 64;
;               store_lines(st, pn_[0], pn_[1], fr, fq, xnew + seg, DM);
;               if (XS) store_lines(st, ps_[0], ps_[1], fr, fq, xs + seg, DM); }
.LBB0_903:
	s_or_b64 exec, exec, s[40:41]
	s_or_b32 s40, s0, 32
	s_ashr_i32 s41, s40, 31
	s_lshl_b64 s[42:43], s[40:41], 10
	s_add_u32 s42, s42, s36
	s_addc_u32 s43, s43, s37
	s_lshl_b64 s[42:43], s[42:43], 1
	ds_read_b128 v[76:79], v219
	s_add_u32 s44, s100, s42
	s_addc_u32 s45, s101, s43
	v_lshl_add_u64 v[74:75], s[44:45], 0, v[162:163]
	v_lshl_add_u64 v[80:81], v[142:143], 1, v[74:75]
	s_waitcnt lgkmcnt(0)
	global_store_dwordx4 v[80:81], v[76:79], off
	s_and_saveexec_b64 s[44:45], s[4:5]
	s_cbranch_execz .LBB0_905
	ds_write_b128 v221, v[30:33]
	ds_write_b128 v221, v[22:25] offset:64

; #define PG8_LAS __attribute__((address_space(3)))
; __device__ __forceinline__ void store_lines(PG8_LAS unsigned char* stg, const u32x4 P0, const u32x4 P1, int fr, int fq, bf16_t* seg0, int pitch) {
;     const int ln = fq * 16 + fr;
; #pragma unroll
;     for (int h = 0; h < 2; ++h) {
;         if ((fr >> 3) == h) { *(PG8_LAS u32x4*)(stg + (fr & 7) * 128 + fq * 16) = P0; *(PG8_LAS u32x4*)(stg + (fr & 7) * 128 + 64 + fq * 16) = P1; }
;         __builtin_amdgcn_wave_barrier(); asm volatile("" ::: "memory");
;         const u32x4 v = *(const PG8_LAS u32x4*)(stg + ln * 16);
;         __builtin_amdgcn_wave_barrier(); asm volatile("" ::: "memory");
;         *(u32x4*)(seg0 + (size_t)(8 * h + (ln >> 3)) * pitch + (ln & 7) * 8) = v; }
;     __device__ __forceinline__ void operator()(const f32x4 (&acc)[2][2][4][2], const Unit& u, int wr, int wc, int fr, int fq) const {
;     ...
;             { const size_t seg = (size_t)(row - fr) * DM + u.pn * BM + wc * 64;
;               store_lines(st, pn_[0], pn_[1], fr, fq, xnew + seg, DM);
;               if (XS) store_lines(st, ps_[0], ps_[1], fr, fq, xs + seg, DM); }
.LBB0_913:
	s_or_b64 exec, exec, s[40:41]
	s_or_b32 s0, s0, 48
	s_ashr_i32 s1, s0, 31
	s_lshl_b64 s[40:41], s[0:1], 10
	s_add_u32 s36, s40, s36
	s_addc_u32 s37, s41, s37
	s_lshl_b64 s[36:37], s[36:37], 1
	ds_read_b128 v[36:39], v219
	s_add_u32 s40, s100, s36
	s_addc_u32 s41, s101, s37
	v_lshl_add_u64 v[34:35], s[40:41], 0, v[162:163]
	v_lshl_add_u64 v[40:41], v[142:143], 1, v[34:35]
	s_waitcnt lgkmcnt(0)
	global_store_dwordx4 v[40:41], v[36:39], off
	s_and_saveexec_b64 s[40:41], s[4:5]
	s_cbranch_execz .LBB0_915
	ds_write_b128 v221, v[14:17]
	ds_write_b128 v221, v[6:9] offset:64

; #define PG8_LAS __attribute__((address_space(3)))
; __device__ __forceinline__ u32x4 pack8(const f32x4 a, const f32x4 b) { u32x4 w; w.x = cvt_pk_bf16(a[0], a[1]); w.y = cvt_pk_bf16(a[2], a[3]); w.z = cvt_pk_bf16(b[0], b[1]); w.w = cvt_pk_bf16(b[2], b[3]); return w; }
;     __device__ __forceinline__ void operator()(const f32x4 (&acc)[2][2][4][2], const Unit& u, int wr, int wc, int fr, int fq) const {
;         asm volatile("" : "+v"(fr), "+v"(fq));
;         const int b = u.pm >> 5, col0 = u.pn * BM + wc * 64 + fq * 8;
;         PG8_LAS unsigned char* st = stg + (wr * 4 + wc) * 1024;
;         f32x4 gv[2][2], cs[2][2];
; #pragma unroll
;         for (int bj = 0; bj < 2; ++bj)
; #pragma unroll
;             for (int n = 0; n < 2; ++n) { const int c = col0 + bj * 32 + 4 * n; gv[bj][n] = *(const f32x4*)(gate + (size_t)b * NMODC + c) * (HALFG ? 0.5f : 1.0f);
;                 cs[bj][n] = (f32x4){0.f, 0.f, 0.f, 0.f}; if (XS) cs[bj][n] = *(const f32x4*)(gcol + c) * (*(const f32x4*)(scm + (size_t)b * NMODC + c) + 1.0f); }
;         u32x4 c16[2], n16[2]; f32x4 c32[2][2], n32[2][2];
;     ...
;         RES_LOAD(c16, c32, 0);
; #pragma unroll
;         for (int r = 0; r < 8; ++r) { const int ai = r >> 2, m = r & 3; const int row = EPI_ROW; float sq = 0.f;
;             if (r < 7) RES_LOAD(n16, n32, r + 1);
;             u32x4 pn_[2], ps_[2];
; #pragma unroll
;             for (int bj = 0; bj < 2; ++bj) {
;                 f32x4 o0, o1;
;                 if (XOLD16) unpack8(c16[bj], o0, o1); else { o0 = c32[bj][0]; o1 = c32[bj][1]; }
;                 const f32x4 v0 = o0 + gv[bj][0] * acc[ai][bj][m][0], v1 = o1 + gv[bj][1] * acc[ai][bj][m][1];
;                 pn_[bj] = pack8(v0, v1);
;                 sq += ((v0[0] * v0[0] + v0[1] * v0[1]) + (v0[2] * v0[2] + v0[3] * v0[3])) + ((v1[0] * v1[0] + v1[1] * v1[1]) + (v1[2] * v1[2] + v1[3] * v1[3]));
;                 if (XS) ps_[bj] = pack8(v0 * cs[bj][0], v1 * cs[bj][1]); }
.LBB0_1072:
	s_mov_b32 s98, s34
	v_readlane_b32 s34, v254, 1
	v_readlane_b32 s35, v254, 2
	s_lshl_b32 s0, s10, 8
	s_or_b32 s0, s0, s57
	s_lshl_b32 s1, s98, 8
	s_add_i32 s1, s1, s54
	s_load_dwordx2 s[100:101], s[34:35], 0x88
	s_ashr_i32 s4, s98, 5
	s_mul_i32 s4, s4, 0x9000
	s_add_u32 s6, s51, s4
	s_addc_u32 s7, s52, 0
	s_lshl_b32 s4, s0, 2
	s_add_u32 s6, s6, s4
	s_addc_u32 s7, s7, 0
	v_lshlrev_b32_e32 v188, 5, v190
	global_load_dwordx4 v[168:171], v188, s[6:7]
	global_load_dwordx4 v[164:167], v188, s[6:7] offset:16
	global_load_dwordx4 v[160:163], v188, s[6:7] offset:128
	global_load_dwordx4 v[156:159], v188, s[6:7] offset:144
	s_lshl_b32 s4, s1, 11
	s_lshl_b32 s5, s0, 1
	s_add_u32 s4, s4, s5
	s_add_u32 s36, s78, 0x18000000
	s_addc_u32 s37, s79, 0
	s_add_u32 s36, s36, s4
	s_addc_u32 s37, s37, 0
	v_lshlrev_b32_e32 v189, 11, v1
	v_lshl_add_u32 v189, v190, 4, v189
	global_load_dwordx4 v[196:199], v189, s[36:37]
	global_load_dwordx4 v[200:203], v189, s[36:37] offset:64
	s_add_u32 s36, s36, 0x8000
	s_addc_u32 s37, s37, 0
	global_load_dwordx4 v[204:207], v189, s[36:37]
	global_load_dwordx4 v[208:211], v189, s[36:37] offset:64
	s_add_u32 s36, s36, 0x8000
	s_addc_u32 s37, s37, 0
	global_load_dwordx4 v[212:215], v189, s[36:37]
	global_load_dwordx4 v[216:219], v189, s[36:37] offset:64
	s_add_u32 s36, s36, 0x8000
	s_addc_u32 s37, s37, 0
	global_load_dwordx4 v[220:223], v189, s[36:37]
	global_load_dwordx4 v[224:227], v189, s[36:37] offset:64
	s_add_u32 s36, s36, 0x28000
	s_addc_u32 s37, s37, 0
	global_load_dwordx4 v[228:231], v189, s[36:37]
	global_load_dwordx4 v[232:235], v189, s[36:37] offset:64
	s_add_u32 s36, s36, 0x8000
	s_addc_u32 s37, s37, 0
	global_load_dwordx4 v[236:239], v189, s[36:37]
	global_load_dwordx4 v[240:243], v189, s[36:37] offset:64
	s_add_u32 s36, s36, 0x8000
	s_addc_u32 s37, s37, 0
	global_load_dwordx4 v[244:247], v189, s[36:37]
	global_load_dwordx4 v[248:251], v189, s[36:37] offset:64
	s_add_u32 s36, s36, 0x8000
	s_addc_u32 s37, s37, 0
	global_load_dwordx4 v[130:133], v189, s[36:37]
	global_load_dwordx4 v[134:137], v189, s[36:37] offset:64
	v_xor_b32_e32 v255, 16, v195
	v_xor_b32_e32 v252, 32, v195
	v_lshlrev_b32_e32 v255, 2, v255
	v_lshlrev_b32_e32 v252, 2, v252
	v_lshlrev_b32_e32 v146, 6, v1
	s_waitcnt vmcnt(16)
	v_pk_mul_f32 v[156:157], v[156:157], 0.5 op_sel_hi:[1,0]
	v_pk_mul_f32 v[158:159], v[158:159], 0.5 op_sel_hi:[1,0]
	v_pk_mul_f32 v[160:161], v[160:161], 0.5 op_sel_hi:[1,0]
	v_pk_mul_f32 v[162:163], v[162:163], 0.5 op_sel_hi:[1,0]
	v_pk_mul_f32 v[164:165], v[164:165], 0.5 op_sel_hi:[1,0]
	v_pk_mul_f32 v[166:167], v[166:167], 0.5 op_sel_hi:[1,0]
	v_pk_mul_f32 v[168:169], v[168:169], 0.5 op_sel_hi:[1,0]
	v_pk_mul_f32 v[170:171], v[170:171], 0.5 op_sel_hi:[1,0]
	s_waitcnt vmcnt(14)
	v_lshlrev_b32_e32 v184, 16, v196
	v_and_b32_e32 v185, 0xffff0000, v196
	v_lshlrev_b32_e32 v186, 16, v197
	v_and_b32_e32 v187, 0xffff0000, v197
	v_lshlrev_b32_e32 v180, 16, v198
	v_and_b32_e32 v181, 0xffff0000, v198
	v_lshlrev_b32_e32 v182, 16, v199
	v_and_b32_e32 v183, 0xffff0000, v199
	v_lshlrev_b32_e32 v176, 16, v200
	v_and_b32_e32 v177, 0xffff0000, v200
	v_lshlrev_b32_e32 v178, 16, v201
	v_and_b32_e32 v179, 0xffff0000, v201
	v_lshlrev_b32_e32 v172, 16, v202
	v_and_b32_e32 v173, 0xffff0000, v202
	v_lshlrev_b32_e32 v174, 16, v203
	v_and_b32_e32 v175, 0xffff0000, v203
	v_pk_fma_f32 v[114:115], v[114:115], v[156:157], v[172:173]
	v_pk_fma_f32 v[116:117], v[116:117], v[158:159], v[174:175]
	v_pk_fma_f32 v[118:119], v[118:119], v[160:161], v[176:177]
	v_pk_fma_f32 v[120:121], v[120:121], v[162:163], v[178:179]
	v_pk_fma_f32 v[122:123], v[122:123], v[164:165], v[180:181]
	v_pk_fma_f32 v[124:125], v[124:125], v[166:167], v[182:183]
	v_pk_fma_f32 v[126:127], v[126:127], v[168:169], v[184:185]
	v_pk_fma_f32 v[128:129], v[128:129], v[170:171], v[186:187]
	v_mul_f32_e32 v172, v127, v127
	v_mul_f32_e32 v173, v129, v129
	v_fmac_f32_e32 v172, v126, v126
	v_fmac_f32_e32 v173, v128, v128
	v_add_f32_e32 v172, v172, v173
	v_mul_f32_e32 v173, v123, v123
	v_mul_f32_e32 v174, v125, v125
	v_fmac_f32_e32 v173, v122, v122
	v_fmac_f32_e32 v174, v124, v124
	v_add_f32_e32 v173, v173, v174
	v_add_f32_e32 v172, v172, v173
	v_mul_f32_e32 v173, v119, v119
	v_mul_f32_e32 v174, v121, v121
	v_fmac_f32_e32 v173, v118, v118
	v_fmac_f32_e32 v174, v120, v120
	v_add_f32_e32 v173, v173, v174
	v_mul_f32_e32 v174, v115, v115
	v_mul_f32_e32 v175, v117, v117
	v_fmac_f32_e32 v174, v114, v114
	v_fmac_f32_e32 v175, v116, v116
	v_add_f32_e32 v174, v174, v175
	v_add_f32_e32 v173, v173, v174
	v_add_f32_e32 v196, v172, v173
	s_waitcnt vmcnt(12)
	v_lshlrev_b32_e32 v184, 16, v204
	v_and_b32_e32 v185, 0xffff0000, v204
	v_lshlrev_b32_e32 v186, 16, v205
	v_and_b32_e32 v187, 0xffff0000, v205
	v_lshlrev_b32_e32 v180, 16, v206
	v_and_b32_e32 v181, 0xffff0000, v206
	v_lshlrev_b32_e32 v182, 16, v207
	v_and_b32_e32 v183, 0xffff0000, v207
	v_lshlrev_b32_e32 v176, 16, v208
	v_and_b32_e32 v177, 0xffff0000, v208
	v_lshlrev_b32_e32 v178, 16, v209
	v_and_b32_e32 v179, 0xffff0000, v209
	v_lshlrev_b32_e32 v172, 16, v210
	v_and_b32_e32 v173, 0xffff0000, v210
	v_lshlrev_b32_e32 v174, 16, v211
	v_and_b32_e32 v175, 0xffff0000, v211
	v_pk_fma_f32 v[98:99], v[98:99], v[156:157], v[172:173]
	v_pk_fma_f32 v[100:101], v[100:101], v[158:159], v[174:175]
	v_pk_fma_f32 v[102:103], v[102:103], v[160:161], v[176:177]
	v_pk_fma_f32 v[104:105], v[104:105], v[162:163], v[178:179]
	v_pk_fma_f32 v[106:107], v[106:107], v[164:165], v[180:181]
	v_pk_fma_f32 v[108:109], v[108:109], v[166:167], v[182:183]
	v_pk_fma_f32 v[110:111], v[110:111], v[168:169], v[184:185]
	v_pk_fma_f32 v[112:113], v[112:113], v[170:171], v[186:187]
	v_mul_f32_e32 v172, v111, v111
	v_mul_f32_e32 v173, v113, v113
	v_fmac_f32_e32 v172, v110, v110
	v_fmac_f32_e32 v173, v112, v112
	v_add_f32_e32 v172, v172, v173
	v_mul_f32_e32 v173, v107, v107
	v_mul_f32_e32 v174, v109, v109
	v_fmac_f32_e32 v173, v106, v106
	v_fmac_f32_e32 v174, v108, v108
	v_add_f32_e32 v173, v173, v174
	v_add_f32_e32 v172, v172, v173
	v_mul_f32_e32 v173, v103, v103
	v_mul_f32_e32 v174, v105, v105
	v_fmac_f32_e32 v173, v102, v102
	v_fmac_f32_e32 v174, v104, v104
	v_add_f32_e32 v173, v173, v174
	v_mul_f32_e32 v174, v99, v99
	v_mul_f32_e32 v175, v101, v101
	v_fmac_f32_e32 v174, v98, v98
	v_fmac_f32_e32 v175, v100, v100
	v_add_f32_e32 v174, v174, v175
	v_add_f32_e32 v173, v173, v174
	v_add_f32_e32 v204, v172, v173
	s_waitcnt vmcnt(10)
; __device__ __forceinline__ u32x4 pack8(const f32x4 a, const f32x4 b) { u32x4 w; w.x = cvt_pk_bf16(a[0], a[1]); w.y = cvt_pk_bf16(a[2], a[3]); w.z = cvt_pk_bf16(b[0], b[1]); w.w = cvt_pk_bf16(b[2], b[3]); return w; }
;     __device__ __forceinline__ void operator()(const f32x4 (&acc)[2][2][4][2], const Unit& u, int wr, int wc, int fr, int fq) const {
;     ...
;         for (int r = 0; r < 8; ++r) { const int ai = r >> 2, m = r & 3; const int row = EPI_ROW; float sq = 0.f;
;             if (r < 7) RES_LOAD(n16, n32, r + 1);
;             u32x4 pn_[2], ps_[2];
; #pragma unroll
;             for (int bj = 0; bj < 2; ++bj) {
;                 f32x4 o0, o1;
;                 if (XOLD16) unpack8(c16[bj], o0, o1); else { o0 = c32[bj][0]; o1 = c32[bj][1]; }
;                 const f32x4 v0 = o0 + gv[bj][0] * acc[ai][bj][m][0], v1 = o1 + gv[bj][1] * acc[ai][bj][m][1];
;                 pn_[bj] = pack8(v0, v1);
;                 sq += ((v0[0] * v0[0] + v0[1] * v0[1]) + (v0[2] * v0[2] + v0[3] * v0[3])) + ((v1[0] * v1[0] + v1[1] * v1[1]) + (v1[2] * v1[2] + v1[3] * v1[3]));
;                 if (XS) ps_[bj] = pack8(v0 * cs[bj][0], v1 * cs[bj][1]); }
	v_lshlrev_b32_e32 v184, 16, v212
	v_and_b32_e32 v185, 0xffff0000, v212
	v_lshlrev_b32_e32 v186, 16, v213
	v_and_b32_e32 v187, 0xffff0000, v213
	v_lshlrev_b32_e32 v180, 16, v214
	v_and_b32_e32 v181, 0xffff0000, v214
	v_lshlrev_b32_e32 v182, 16, v215
	v_and_b32_e32 v183, 0xffff0000, v215
	v_lshlrev_b32_e32 v176, 16, v216
	v_and_b32_e32 v177, 0xffff0000, v216
	v_lshlrev_b32_e32 v178, 16, v217
	v_and_b32_e32 v179, 0xffff0000, v217
	v_lshlrev_b32_e32 v172, 16, v218
	v_and_b32_e32 v173, 0xffff0000, v218
	v_lshlrev_b32_e32 v174, 16, v219
	v_and_b32_e32 v175, 0xffff0000, v219
	v_pk_fma_f32 v[82:83], v[82:83], v[156:157], v[172:173]
	v_pk_fma_f32 v[84:85], v[84:85], v[158:159], v[174:175]
	v_pk_fma_f32 v[86:87], v[86:87], v[160:161], v[176:177]
	v_pk_fma_f32 v[88:89], v[88:89], v[162:163], v[178:179]
	v_pk_fma_f32 v[90:91], v[90:91], v[164:165], v[180:181]
	v_pk_fma_f32 v[92:93], v[92:93], v[166:167], v[182:183]
	v_pk_fma_f32 v[94:95], v[94:95], v[168:169], v[184:185]
	v_pk_fma_f32 v[96:97], v[96:97], v[170:171], v[186:187]
	v_mul_f32_e32 v172, v95, v95
	v_mul_f32_e32 v173, v97, v97
	v_fmac_f32_e32 v172, v94, v94
	v_fmac_f32_e32 v173, v96, v96
	v_add_f32_e32 v172, v172, v173
	v_mul_f32_e32 v173, v91, v91
	v_mul_f32_e32 v174, v93, v93
	v_fmac_f32_e32 v173, v90, v90
	v_fmac_f32_e32 v174, v92, v92
	v_add_f32_e32 v173, v173, v174
	v_add_f32_e32 v172, v172, v173
	v_mul_f32_e32 v173, v87, v87
	v_mul_f32_e32 v174, v89, v89
	v_fmac_f32_e32 v173, v86, v86
	v_fmac_f32_e32 v174, v88, v88
	v_add_f32_e32 v173, v173, v174
	v_mul_f32_e32 v174, v83, v83
	v_mul_f32_e32 v175, v85, v85
	v_fmac_f32_e32 v174, v82, v82
	v_fmac_f32_e32 v175, v84, v84
	v_add_f32_e32 v174, v174, v175
	v_add_f32_e32 v173, v173, v174
	v_add_f32_e32 v212, v172, v173
	s_waitcnt vmcnt(8)
	v_lshlrev_b32_e32 v184, 16, v220
	v_and_b32_e32 v185, 0xffff0000, v220
	v_lshlrev_b32_e32 v186, 16, v221
	v_and_b32_e32 v187, 0xffff0000, v221
	v_lshlrev_b32_e32 v180, 16, v222
	v_and_b32_e32 v181, 0xffff0000, v222
	v_lshlrev_b32_e32 v182, 16, v223
	v_and_b32_e32 v183, 0xffff0000, v223
	v_lshlrev_b32_e32 v176, 16, v224
	v_and_b32_e32 v177, 0xffff0000, v224
	v_lshlrev_b32_e32 v178, 16, v225
	v_and_b32_e32 v179, 0xffff0000, v225
	v_lshlrev_b32_e32 v172, 16, v226
	v_and_b32_e32 v173, 0xffff0000, v226
	v_lshlrev_b32_e32 v174, 16, v227
	v_and_b32_e32 v175, 0xffff0000, v227
	v_pk_fma_f32 v[66:67], v[66:67], v[156:157], v[172:173]
	v_pk_fma_f32 v[68:69], v[68:69], v[158:159], v[174:175]
	v_pk_fma_f32 v[70:71], v[70:71], v[160:161], v[176:177]
	v_pk_fma_f32 v[72:73], v[72:73], v[162:163], v[178:179]
	v_pk_fma_f32 v[74:75], v[74:75], v[164:165], v[180:181]
	v_pk_fma_f32 v[76:77], v[76:77], v[166:167], v[182:183]
	v_pk_fma_f32 v[78:79], v[78:79], v[168:169], v[184:185]
	v_pk_fma_f32 v[80:81], v[80:81], v[170:171], v[186:187]
	v_mul_f32_e32 v172, v79, v79
	v_mul_f32_e32 v173, v81, v81
	v_fmac_f32_e32 v172, v78, v78
	v_fmac_f32_e32 v173, v80, v80
	v_add_f32_e32 v172, v172, v173
	v_mul_f32_e32 v173, v75, v75
	v_mul_f32_e32 v174, v77, v77
	v_fmac_f32_e32 v173, v74, v74
	v_fmac_f32_e32 v174, v76, v76
	v_add_f32_e32 v173, v173, v174
	v_add_f32_e32 v172, v172, v173
	v_mul_f32_e32 v173, v71, v71
	v_mul_f32_e32 v174, v73, v73
	v_fmac_f32_e32 v173, v70, v70
	v_fmac_f32_e32 v174, v72, v72
	v_add_f32_e32 v173, v173, v174
	v_mul_f32_e32 v174, v67, v67
	v_mul_f32_e32 v175, v69, v69
	v_fmac_f32_e32 v174, v66, v66
	v_fmac_f32_e32 v175, v68, v68
	v_add_f32_e32 v174, v174, v175
	v_add_f32_e32 v173, v173, v174
	v_add_f32_e32 v220, v172, v173
	s_waitcnt vmcnt(6)
	v_lshlrev_b32_e32 v184, 16, v228
	v_and_b32_e32 v185, 0xffff0000, v228
	v_lshlrev_b32_e32 v186, 16, v229
	v_and_b32_e32 v187, 0xffff0000, v229
	v_lshlrev_b32_e32 v180, 16, v230
	v_and_b32_e32 v181, 0xffff0000, v230
	v_lshlrev_b32_e32 v182, 16, v231
	v_and_b32_e32 v183, 0xffff0000, v231
	v_lshlrev_b32_e32 v176, 16, v232
	v_and_b32_e32 v177, 0xffff0000, v232
	v_lshlrev_b32_e32 v178, 16, v233
	v_and_b32_e32 v179, 0xffff0000, v233
	v_lshlrev_b32_e32 v172, 16, v234
	v_and_b32_e32 v173, 0xffff0000, v234
	v_lshlrev_b32_e32 v174, 16, v235
	v_and_b32_e32 v175, 0xffff0000, v235
	v_pk_fma_f32 v[50:51], v[50:51], v[156:157], v[172:173]
	v_pk_fma_f32 v[52:53], v[52:53], v[158:159], v[174:175]
	v_pk_fma_f32 v[54:55], v[54:55], v[160:161], v[176:177]
	v_pk_fma_f32 v[56:57], v[56:57], v[162:163], v[178:179]
	v_pk_fma_f32 v[58:59], v[58:59], v[164:165], v[180:181]
	v_pk_fma_f32 v[60:61], v[60:61], v[166:167], v[182:183]
	v_pk_fma_f32 v[62:63], v[62:63], v[168:169], v[184:185]
	v_pk_fma_f32 v[64:65], v[64:65], v[170:171], v[186:187]
	v_mul_f32_e32 v172, v63, v63
	v_mul_f32_e32 v173, v65, v65
	v_fmac_f32_e32 v172, v62, v62
	v_fmac_f32_e32 v173, v64, v64
	v_add_f32_e32 v172, v172, v173
	v_mul_f32_e32 v173, v59, v59
	v_mul_f32_e32 v174, v61, v61
	v_fmac_f32_e32 v173, v58, v58
	v_fmac_f32_e32 v174, v60, v60
	v_add_f32_e32 v173, v173, v174
	v_add_f32_e32 v172, v172, v173
	v_mul_f32_e32 v173, v55, v55
	v_mul_f32_e32 v174, v57, v57
	v_fmac_f32_e32 v173, v54, v54
	v_fmac_f32_e32 v174, v56, v56
	v_add_f32_e32 v173, v173, v174
	v_mul_f32_e32 v174, v51, v51
	v_mul_f32_e32 v175, v53, v53
	v_fmac_f32_e32 v174, v50, v50
	v_fmac_f32_e32 v175, v52, v52
	v_add_f32_e32 v174, v174, v175
	v_add_f32_e32 v173, v173, v174
	v_add_f32_e32 v228, v172, v173
	s_waitcnt vmcnt(4)
; __device__ __forceinline__ u32x4 pack8(const f32x4 a, const f32x4 b) { u32x4 w; w.x = cvt_pk_bf16(a[0], a[1]); w.y = cvt_pk_bf16(a[2], a[3]); w.z = cvt_pk_bf16(b[0], b[1]); w.w = cvt_pk_bf16(b[2], b[3]); return w; }
;     __device__ __forceinline__ void operator()(const f32x4 (&acc)[2][2][4][2], const Unit& u, int wr, int wc, int fr, int fq) const {
;     ...
;         for (int r = 0; r < 8; ++r) { const int ai = r >> 2, m = r & 3; const int row = EPI_ROW; float sq = 0.f;
;             if (r < 7) RES_LOAD(n16, n32, r + 1);
;             u32x4 pn_[2], ps_[2];
; #pragma unroll
;             for (int bj = 0; bj < 2; ++bj) {
;                 f32x4 o0, o1;
;                 if (XOLD16) unpack8(c16[bj], o0, o1); else { o0 = c32[bj][0]; o1 = c32[bj][1]; }
;                 const f32x4 v0 = o0 + gv[bj][0] * acc[ai][bj][m][0], v1 = o1 + gv[bj][1] * acc[ai][bj][m][1];
;                 pn_[bj] = pack8(v0, v1);
;                 sq += ((v0[0] * v0[0] + v0[1] * v0[1]) + (v0[2] * v0[2] + v0[3] * v0[3])) + ((v1[0] * v1[0] + v1[1] * v1[1]) + (v1[2] * v1[2] + v1[3] * v1[3]));
;                 if (XS) ps_[bj] = pack8(v0 * cs[bj][0], v1 * cs[bj][1]); }
;             { const size_t seg = (size_t)(row - fr) * DM + u.pn * BM + wc * 64;
;               store_lines(st, pn_[0], pn_[1], fr, fq, xnew + seg, DM);
;               if (XS) store_lines(st, ps_[0], ps_[1], fr, fq, xs + seg, DM); }
;             sq += __shfl_xor(sq, 16); sq += __shfl_xor(sq, 32);
	v_lshlrev_b32_e32 v184, 16, v236
	v_and_b32_e32 v185, 0xffff0000, v236
	v_lshlrev_b32_e32 v186, 16, v237
	v_and_b32_e32 v187, 0xffff0000, v237
	v_lshlrev_b32_e32 v180, 16, v238
	v_and_b32_e32 v181, 0xffff0000, v238
	v_lshlrev_b32_e32 v182, 16, v239
	v_and_b32_e32 v183, 0xffff0000, v239
	v_lshlrev_b32_e32 v176, 16, v240
	v_and_b32_e32 v177, 0xffff0000, v240
	v_lshlrev_b32_e32 v178, 16, v241
	v_and_b32_e32 v179, 0xffff0000, v241
	v_lshlrev_b32_e32 v172, 16, v242
	v_and_b32_e32 v173, 0xffff0000, v242
	v_lshlrev_b32_e32 v174, 16, v243
	v_and_b32_e32 v175, 0xffff0000, v243
	v_pk_fma_f32 v[34:35], v[34:35], v[156:157], v[172:173]
	v_pk_fma_f32 v[36:37], v[36:37], v[158:159], v[174:175]
	v_pk_fma_f32 v[38:39], v[38:39], v[160:161], v[176:177]
	v_pk_fma_f32 v[40:41], v[40:41], v[162:163], v[178:179]
	v_pk_fma_f32 v[42:43], v[42:43], v[164:165], v[180:181]
	v_pk_fma_f32 v[44:45], v[44:45], v[166:167], v[182:183]
	v_pk_fma_f32 v[46:47], v[46:47], v[168:169], v[184:185]
	v_pk_fma_f32 v[48:49], v[48:49], v[170:171], v[186:187]
	v_mul_f32_e32 v172, v47, v47
	v_mul_f32_e32 v173, v49, v49
	v_fmac_f32_e32 v172, v46, v46
	v_fmac_f32_e32 v173, v48, v48
	v_add_f32_e32 v172, v172, v173
	v_mul_f32_e32 v173, v43, v43
	v_mul_f32_e32 v174, v45, v45
	v_fmac_f32_e32 v173, v42, v42
	v_fmac_f32_e32 v174, v44, v44
	v_add_f32_e32 v173, v173, v174
	v_add_f32_e32 v172, v172, v173
	v_mul_f32_e32 v173, v39, v39
	v_mul_f32_e32 v174, v41, v41
	v_fmac_f32_e32 v173, v38, v38
	v_fmac_f32_e32 v174, v40, v40
	v_add_f32_e32 v173, v173, v174
	v_mul_f32_e32 v174, v35, v35
	v_mul_f32_e32 v175, v37, v37
	v_fmac_f32_e32 v174, v34, v34
	v_fmac_f32_e32 v175, v36, v36
	v_add_f32_e32 v174, v174, v175
	v_add_f32_e32 v173, v173, v174
	v_add_f32_e32 v236, v172, v173
	s_waitcnt vmcnt(2)
	v_lshlrev_b32_e32 v184, 16, v244
	v_and_b32_e32 v185, 0xffff0000, v244
	v_lshlrev_b32_e32 v186, 16, v245
	v_and_b32_e32 v187, 0xffff0000, v245
	v_lshlrev_b32_e32 v180, 16, v246
	v_and_b32_e32 v181, 0xffff0000, v246
	v_lshlrev_b32_e32 v182, 16, v247
	v_and_b32_e32 v183, 0xffff0000, v247
	v_lshlrev_b32_e32 v176, 16, v248
	v_and_b32_e32 v177, 0xffff0000, v248
	v_lshlrev_b32_e32 v178, 16, v249
	v_and_b32_e32 v179, 0xffff0000, v249
	v_lshlrev_b32_e32 v172, 16, v250
	v_and_b32_e32 v173, 0xffff0000, v250
	v_lshlrev_b32_e32 v174, 16, v251
	v_and_b32_e32 v175, 0xffff0000, v251
	v_pk_fma_f32 v[18:19], v[18:19], v[156:157], v[172:173]
	v_pk_fma_f32 v[20:21], v[20:21], v[158:159], v[174:175]
	v_pk_fma_f32 v[22:23], v[22:23], v[160:161], v[176:177]
	v_pk_fma_f32 v[24:25], v[24:25], v[162:163], v[178:179]
	v_pk_fma_f32 v[26:27], v[26:27], v[164:165], v[180:181]
	v_pk_fma_f32 v[28:29], v[28:29], v[166:167], v[182:183]
	v_pk_fma_f32 v[30:31], v[30:31], v[168:169], v[184:185]
	v_pk_fma_f32 v[32:33], v[32:33], v[170:171], v[186:187]
	v_mul_f32_e32 v172, v31, v31
	v_mul_f32_e32 v173, v33, v33
	v_fmac_f32_e32 v172, v30, v30
	v_fmac_f32_e32 v173, v32, v32
	v_add_f32_e32 v172, v172, v173
	v_mul_f32_e32 v173, v27, v27
	v_mul_f32_e32 v174, v29, v29
	v_fmac_f32_e32 v173, v26, v26
	v_fmac_f32_e32 v174, v28, v28
	v_add_f32_e32 v173, v173, v174
	v_add_f32_e32 v172, v172, v173
	v_mul_f32_e32 v173, v23, v23
	v_mul_f32_e32 v174, v25, v25
	v_fmac_f32_e32 v173, v22, v22
	v_fmac_f32_e32 v174, v24, v24
	v_add_f32_e32 v173, v173, v174
	v_mul_f32_e32 v174, v19, v19
	v_mul_f32_e32 v175, v21, v21
	v_fmac_f32_e32 v174, v18, v18
	v_fmac_f32_e32 v175, v20, v20
	v_add_f32_e32 v174, v174, v175
	v_add_f32_e32 v173, v173, v174
	v_add_f32_e32 v244, v172, v173
	s_waitcnt vmcnt(0)
	v_lshlrev_b32_e32 v184, 16, v130
	v_and_b32_e32 v185, 0xffff0000, v130
	v_lshlrev_b32_e32 v186, 16, v131
	v_and_b32_e32 v187, 0xffff0000, v131
	v_lshlrev_b32_e32 v180, 16, v132
	v_and_b32_e32 v181, 0xffff0000, v132
	v_lshlrev_b32_e32 v182, 16, v133
	v_and_b32_e32 v183, 0xffff0000, v133
	v_lshlrev_b32_e32 v176, 16, v134
	v_and_b32_e32 v177, 0xffff0000, v134
	v_lshlrev_b32_e32 v178, 16, v135
	v_and_b32_e32 v179, 0xffff0000, v135
	v_lshlrev_b32_e32 v172, 16, v136
	v_and_b32_e32 v173, 0xffff0000, v136
	v_lshlrev_b32_e32 v174, 16, v137
	v_and_b32_e32 v175, 0xffff0000, v137
	v_pk_fma_f32 v[2:3], v[2:3], v[156:157], v[172:173]
	v_pk_fma_f32 v[4:5], v[4:5], v[158:159], v[174:175]
	v_pk_fma_f32 v[6:7], v[6:7], v[160:161], v[176:177]
	v_pk_fma_f32 v[8:9], v[8:9], v[162:163], v[178:179]
	v_pk_fma_f32 v[10:11], v[10:11], v[164:165], v[180:181]
	v_pk_fma_f32 v[12:13], v[12:13], v[166:167], v[182:183]
	v_pk_fma_f32 v[14:15], v[14:15], v[168:169], v[184:185]
	v_pk_fma_f32 v[16:17], v[16:17], v[170:171], v[186:187]
	v_mul_f32_e32 v172, v15, v15
	v_mul_f32_e32 v173, v17, v17
	v_fmac_f32_e32 v172, v14, v14
	v_fmac_f32_e32 v173, v16, v16
	v_add_f32_e32 v172, v172, v173
	v_mul_f32_e32 v173, v11, v11
	v_mul_f32_e32 v174, v13, v13
	v_fmac_f32_e32 v173, v10, v10
	v_fmac_f32_e32 v174, v12, v12
	v_add_f32_e32 v173, v173, v174
	v_add_f32_e32 v172, v172, v173
	v_mul_f32_e32 v173, v7, v7
	v_mul_f32_e32 v174, v9, v9
	v_fmac_f32_e32 v173, v6, v6
	v_fmac_f32_e32 v174, v8, v8
	v_add_f32_e32 v173, v173, v174
	v_mul_f32_e32 v174, v3, v3
	v_mul_f32_e32 v175, v5, v5
	v_fmac_f32_e32 v174, v2, v2
	v_fmac_f32_e32 v175, v4, v4
	v_add_f32_e32 v174, v174, v175
	v_add_f32_e32 v173, v173, v174
	v_add_f32_e32 v130, v172, v173
	ds_bpermute_b32 v197, v255, v196
	ds_bpermute_b32 v205, v255, v204
	ds_bpermute_b32 v213, v255, v212
	ds_bpermute_b32 v221, v255, v220
	ds_bpermute_b32 v229, v255, v228
	ds_bpermute_b32 v237, v255, v236
	ds_bpermute_b32 v245, v255, v244
	ds_bpermute_b32 v131, v255, v130
	s_waitcnt lgkmcnt(0)
;     __device__ __forceinline__ void operator()(const f32x4 (&acc)[2][2][4][2], const Unit& u, int wr, int wc, int fr, int fq) const {
;     ...
;             sq += __shfl_xor(sq, 16); sq += __shfl_xor(sq, 32);
;             if (fq == 0) ssq[(size_t)row * 16 + u.pn * 4 + wc] = sq;
; __device__ __forceinline__ void p10_final(const Args& A, int lane, int wave, float* outp) {
;     ...
;     const int gw = blockIdx.x * 8 + wave, NGW = gridDim.x * 8;
;     for (int m = gw; m < M; m += NGW) { const float rs = pg8::rstd_from(ssq, m);
; #pragma unroll
;         for (int j = 0; j < 2; ++j) { const int c = 8 * lane + 512 * j; f32x4 a, b; pg8::unpack8(*(const u32x4*)(X3 + (size_t)m * DM + c), a, b);
	v_add_f32_e32 v196, v196, v197
	v_add_f32_e32 v204, v204, v205
	v_add_f32_e32 v212, v212, v213
	v_add_f32_e32 v220, v220, v221
	v_add_f32_e32 v228, v228, v229
	v_add_f32_e32 v236, v236, v237
	v_add_f32_e32 v244, v244, v245
	v_add_f32_e32 v130, v130, v131
	ds_bpermute_b32 v197, v252, v196
	ds_bpermute_b32 v205, v252, v204
	ds_bpermute_b32 v213, v252, v212
	ds_bpermute_b32 v221, v252, v220
	ds_bpermute_b32 v229, v252, v228
	ds_bpermute_b32 v237, v252, v236
	ds_bpermute_b32 v245, v252, v244
	ds_bpermute_b32 v131, v252, v130
	s_waitcnt lgkmcnt(0)
	v_add_f32_e32 v196, v196, v197
	v_add_f32_e32 v204, v204, v205
	v_add_f32_e32 v212, v212, v213
	v_add_f32_e32 v220, v220, v221
	v_add_f32_e32 v228, v228, v229
	v_add_f32_e32 v236, v236, v237
	v_add_f32_e32 v244, v244, v245
	v_add_f32_e32 v130, v130, v131
	s_lshl_b32 s4, s1, 6
	s_lshl_b32 s5, s10, 4
	s_add_u32 s4, s4, s5
	s_lshl_b32 s5, s53, 2
	s_add_u32 s4, s4, s5
	s_add_u32 s38, s16, s4
	s_addc_u32 s39, s17, 0
	s_add_u32 s36, s38, 0x2000
	s_addc_u32 s37, s39, 0
	s_mov_b64 exec, 0xffff
	global_store_dword v146, v196, s[38:39] offset:0 sc0 sc1
	global_store_dword v146, v204, s[38:39] offset:1024 sc0 sc1
	global_store_dword v146, v212, s[38:39] offset:2048 sc0 sc1
	global_store_dword v146, v220, s[38:39] offset:3072 sc0 sc1
	global_store_dword v146, v228, s[36:37] offset:0 sc0 sc1
	global_store_dword v146, v236, s[36:37] offset:1024 sc0 sc1
	global_store_dword v146, v244, s[36:37] offset:2048 sc0 sc1
	global_store_dword v146, v130, s[36:37] offset:3072 sc0 sc1
	s_mov_b64 exec, -1
	s_waitcnt vmcnt(0)
	s_barrier
	v_cmp_eq_u32_e32 vcc, 0, v0
	s_and_saveexec_b64 s[30:31], vcc
	s_cbranch_execz .Lf9_sync_done
	s_lshl_b32 s4, s98, 2
	s_add_u32 s4, s4, 0x83800
	s_add_u32 s4, s78, s4
	s_addc_u32 s5, s79, 0
	v_mov_b32_e32 v253, 0
	v_mov_b32_e32 v172, 1
	global_atomic_add v253, v172, s[4:5]
	s_mov_b32 s6, 0
.Lf9_spin:
	global_load_dword v173, v253, s[4:5] sc1
	s_waitcnt vmcnt(0)
	v_readfirstlane_b32 s7, v173
	s_nop 3
	s_cmp_ge_u32 s7, 4
	s_cbranch_scc1 .Lf9_sync_done
	s_sleep 1
	s_add_i32 s6, s6, 1
	s_cmp_lt_u32 s6, 0x2000
	s_cbranch_scc1 .Lf9_spin
.Lf9_sync_done:
	s_or_b64 exec, exec, s[30:31]
	s_barrier
	s_waitcnt lgkmcnt(0)
	s_lshl_b32 s4, s0, 2
	s_add_u32 s4, s100, s4
	s_addc_u32 s5, s101, 0
	global_load_dwordx4 v[168:171], v188, s[4:5]
	global_load_dwordx4 v[164:167], v188, s[4:5] offset:16
	global_load_dwordx4 v[160:163], v188, s[4:5] offset:128
	global_load_dwordx4 v[156:159], v188, s[4:5] offset:144
	s_lshl_b32 s4, s1, 6
	s_add_u32 s38, s16, s4
	s_addc_u32 s39, s17, 0
	s_add_u32 s36, s38, 0x2000
	s_addc_u32 s37, s39, 0
	v_mov_b32_e32 v189, 0x358637bd
	global_load_dwordx4 v[196:199], v146, s[38:39] offset:0 sc0 sc1
	global_load_dwordx4 v[200:203], v146, s[38:39] offset:16 sc0 sc1
	global_load_dwordx4 v[204:207], v146, s[38:39] offset:32 sc0 sc1
	global_load_dwordx4 v[208:211], v146, s[38:39] offset:48 sc0 sc1
	global_load_dwordx4 v[212:215], v146, s[38:39] offset:1024 sc0 sc1
	global_load_dwordx4 v[216:219], v146, s[38:39] offset:1040 sc0 sc1
	global_load_dwordx4 v[220:223], v146, s[38:39] offset:1056 sc0 sc1
	global_load_dwordx4 v[224:227], v146, s[38:39] offset:1072 sc0 sc1
	global_load_dwordx4 v[228:231], v146, s[38:39] offset:2048 sc0 sc1
	global_load_dwordx4 v[232:235], v146, s[38:39] offset:2064 sc0 sc1
	global_load_dwordx4 v[236:239], v146, s[38:39] offset:2080 sc0 sc1
	global_load_dwordx4 v[240:243], v146, s[38:39] offset:2096 sc0 sc1
	global_load_dwordx4 v[244:247], v146, s[38:39] offset:3072 sc0 sc1
	global_load_dwordx4 v[248:251], v146, s[38:39] offset:3088 sc0 sc1
	global_load_dwordx4 v[130:133], v146, s[38:39] offset:3104 sc0 sc1
	global_load_dwordx4 v[134:137], v146, s[38:39] offset:3120 sc0 sc1
	s_waitcnt vmcnt(0)
	v_pk_add_f32 v[196:197], v[196:197], v[200:201]
	v_pk_add_f32 v[198:199], v[198:199], v[202:203]
	v_pk_add_f32 v[204:205], v[204:205], v[208:209]
	v_pk_add_f32 v[206:207], v[206:207], v[210:211]
	v_pk_add_f32 v[196:197], v[196:197], v[204:205]
	v_pk_add_f32 v[198:199], v[198:199], v[206:207]
	v_add_f32_e32 v196, v196, v197
	v_add_f32_e32 v198, v198, v199
	v_add_f32_e32 v196, v196, v198
	v_fmamk_f32 v196, v196, 0x3a800000, v189
	v_rsq_f32_e32 v172, v196
	v_pk_add_f32 v[212:213], v[212:213], v[216:217]
	v_pk_add_f32 v[214:215], v[214:215], v[218:219]
	v_pk_add_f32 v[220:221], v[220:221], v[224:225]
	v_pk_add_f32 v[222:223], v[222:223], v[226:227]
	v_pk_add_f32 v[212:213], v[212:213], v[220:221]
	v_pk_add_f32 v[214:215], v[214:215], v[222:223]
	v_add_f32_e32 v212, v212, v213
	v_add_f32_e32 v214, v214, v215
	v_add_f32_e32 v212, v212, v214
	v_fmamk_f32 v212, v212, 0x3a800000, v189
	v_rsq_f32_e32 v173, v212
	v_pk_add_f32 v[228:229], v[228:229], v[232:233]
	v_pk_add_f32 v[230:231], v[230:231], v[234:235]
	v_pk_add_f32 v[236:237], v[236:237], v[240:241]
	v_pk_add_f32 v[238:239], v[238:239], v[242:243]
	v_pk_add_f32 v[228:229], v[228:229], v[236:237]
	v_pk_add_f32 v[230:231], v[230:231], v[238:239]
	v_add_f32_e32 v228, v228, v229
	v_add_f32_e32 v230, v230, v231
	v_add_f32_e32 v228, v228, v230
	v_fmamk_f32 v228, v228, 0x3a800000, v189
	v_rsq_f32_e32 v174, v228
	v_pk_add_f32 v[244:245], v[244:245], v[248:249]
	v_pk_add_f32 v[246:247], v[246:247], v[250:251]
	v_pk_add_f32 v[130:131], v[130:131], v[134:135]
	v_pk_add_f32 v[132:133], v[132:133], v[136:137]
	v_pk_add_f32 v[244:245], v[244:245], v[130:131]
	v_pk_add_f32 v[246:247], v[246:247], v[132:133]
	v_add_f32_e32 v244, v244, v245
	v_add_f32_e32 v246, v246, v247
	v_add_f32_e32 v244, v244, v246
	v_fmamk_f32 v244, v244, 0x3a800000, v189
	v_rsq_f32_e32 v175, v244
	global_load_dwordx4 v[196:199], v146, s[36:37] offset:0 sc0 sc1
	global_load_dwordx4 v[200:203], v146, s[36:37] offset:16 sc0 sc1
	global_load_dwordx4 v[204:207], v146, s[36:37] offset:32 sc0 sc1
	global_load_dwordx4 v[208:211], v146, s[36:37] offset:48 sc0 sc1
	global_load_dwordx4 v[212:215], v146, s[36:37] offset:1024 sc0 sc1
	global_load_dwordx4 v[216:219], v146, s[36:37] offset:1040 sc0 sc1
	global_load_dwordx4 v[220:223], v146, s[36:37] offset:1056 sc0 sc1
	global_load_dwordx4 v[224:227], v146, s[36:37] offset:1072 sc0 sc1
	global_load_dwordx4 v[228:231], v146, s[36:37] offset:2048 sc0 sc1
	global_load_dwordx4 v[232:235], v146, s[36:37] offset:2064 sc0 sc1
	global_load_dwordx4 v[236:239], v146, s[36:37] offset:2080 sc0 sc1
	global_load_dwordx4 v[240:243], v146, s[36:37] offset:2096 sc0 sc1
	global_load_dwordx4 v[244:247], v146, s[36:37] offset:3072 sc0 sc1
	global_load_dwordx4 v[248:251], v146, s[36:37] offset:3088 sc0 sc1
	global_load_dwordx4 v[130:133], v146, s[36:37] offset:3104 sc0 sc1
	global_load_dwordx4 v[134:137], v146, s[36:37] offset:3120 sc0 sc1
	s_waitcnt vmcnt(0)
; #define PG8_LAS __attribute__((address_space(3)))
; __device__ __forceinline__ void store_lines(PG8_LAS unsigned char* stg, const u32x4 P0, const u32x4 P1, int fr, int fq, bf16_t* seg0, int pitch) {
;     const int ln = fq * 16 + fr;
; #pragma unroll
;     for (int h = 0; h < 2; ++h) {
;         if ((fr >> 3) == h) { *(PG8_LAS u32x4*)(stg + (fr & 7) * 128 + fq * 16) = P0; *(PG8_LAS u32x4*)(stg + (fr & 7) * 128 + 64 + fq * 16) = P1; }
;         __builtin_amdgcn_wave_barrier(); asm volatile("" ::: "memory");
;         const u32x4 v = *(const PG8_LAS u32x4*)(stg + ln * 16);
;         __builtin_amdgcn_wave_barrier(); asm volatile("" ::: "memory");
;         *(u32x4*)(seg0 + (size_t)(8 * h + (ln >> 3)) * pitch + (ln & 7) * 8) = v; }
; __device__ __forceinline__ void p10_final(const Args& A, int lane, int wave, float* outp) {
;     ...
;     for (int m = gw; m < M; m += NGW) { const float rs = pg8::rstd_from(ssq, m);
; #pragma unroll
;         for (int j = 0; j < 2; ++j) { const int c = 8 * lane + 512 * j; f32x4 a, b; pg8::unpack8(*(const u32x4*)(X3 + (size_t)m * DM + c), a, b);
;             *(f32x4*)(outp + (size_t)m * DM + c) = (a * rs) * *(const f32x4*)(A.g_final + c); *(f32x4*)(outp + (size_t)m * DM + c + 4) = (b * rs) * *(const f32x4*)(A.g_final + c + 4); } }
	v_pk_add_f32 v[196:197], v[196:197], v[200:201]
	v_pk_add_f32 v[198:199], v[198:199], v[202:203]
	v_pk_add_f32 v[204:205], v[204:205], v[208:209]
	v_pk_add_f32 v[206:207], v[206:207], v[210:211]
	v_pk_add_f32 v[196:197], v[196:197], v[204:205]
	v_pk_add_f32 v[198:199], v[198:199], v[206:207]
	v_add_f32_e32 v196, v196, v197
	v_add_f32_e32 v198, v198, v199
	v_add_f32_e32 v196, v196, v198
	v_fmamk_f32 v196, v196, 0x3a800000, v189
	v_rsq_f32_e32 v176, v196
	v_pk_add_f32 v[212:213], v[212:213], v[216:217]
	v_pk_add_f32 v[214:215], v[214:215], v[218:219]
	v_pk_add_f32 v[220:221], v[220:221], v[224:225]
	v_pk_add_f32 v[222:223], v[222:223], v[226:227]
	v_pk_add_f32 v[212:213], v[212:213], v[220:221]
	v_pk_add_f32 v[214:215], v[214:215], v[222:223]
	v_add_f32_e32 v212, v212, v213
	v_add_f32_e32 v214, v214, v215
	v_add_f32_e32 v212, v212, v214
	v_fmamk_f32 v212, v212, 0x3a800000, v189
	v_rsq_f32_e32 v177, v212
	v_pk_add_f32 v[228:229], v[228:229], v[232:233]
	v_pk_add_f32 v[230:231], v[230:231], v[234:235]
	v_pk_add_f32 v[236:237], v[236:237], v[240:241]
	v_pk_add_f32 v[238:239], v[238:239], v[242:243]
	v_pk_add_f32 v[228:229], v[228:229], v[236:237]
	v_pk_add_f32 v[230:231], v[230:231], v[238:239]
	v_add_f32_e32 v228, v228, v229
	v_add_f32_e32 v230, v230, v231
	v_add_f32_e32 v228, v228, v230
	v_fmamk_f32 v228, v228, 0x3a800000, v189
	v_rsq_f32_e32 v178, v228
	v_pk_add_f32 v[244:245], v[244:245], v[248:249]
	v_pk_add_f32 v[246:247], v[246:247], v[250:251]
	v_pk_add_f32 v[130:131], v[130:131], v[134:135]
	v_pk_add_f32 v[132:133], v[132:133], v[136:137]
	v_pk_add_f32 v[244:245], v[244:245], v[130:131]
	v_pk_add_f32 v[246:247], v[246:247], v[132:133]
	v_add_f32_e32 v244, v244, v245
	v_add_f32_e32 v246, v246, v247
	v_add_f32_e32 v244, v244, v246
	v_fmamk_f32 v244, v244, 0x3a800000, v189
	v_rsq_f32_e32 v179, v244
	s_lshl_b32 s4, s54, 7
	s_lshl_b32 s5, s53, 11
	s_add_i32 s4, s4, s5
	s_add_i32 s4, s4, 0x20000
	v_lshlrev_b32_e32 v228, 7, v1
	v_lshl_add_u32 v228, v190, 5, v228
	v_add_u32_e32 v228, s4, v228
	v_lshl_add_u32 v229, v195, 4, s4
	v_lshrrev_b32_e32 v230, 3, v195
	v_lshlrev_b32_e32 v230, 12, v230
	v_and_b32_e32 v231, 7, v195
	v_lshl_add_u32 v230, v231, 4, v230
	v_add_u32_e32 v231, 0x8000, v230
	s_lshl_b32 s4, s1, 12
	s_lshl_b32 s5, s0, 2
	s_add_u32 s4, s4, s5
	s_add_u32 s34, s76, s4
	s_addc_u32 s35, s77, 0
	v_mul_f32_e32 v196, v172, v114
	v_mul_f32_e32 v197, v172, v115
	v_mul_f32_e32 v198, v172, v116
	v_mul_f32_e32 v199, v172, v117
	v_mul_f32_e32 v200, v172, v118
	v_mul_f32_e32 v201, v172, v119
	v_mul_f32_e32 v202, v172, v120
	v_mul_f32_e32 v203, v172, v121
	v_mul_f32_e32 v204, v172, v122
	v_mul_f32_e32 v205, v172, v123
	v_mul_f32_e32 v206, v172, v124
	v_mul_f32_e32 v207, v172, v125
	v_mul_f32_e32 v208, v172, v126
	v_mul_f32_e32 v209, v172, v127
	v_mul_f32_e32 v210, v172, v128
	v_mul_f32_e32 v211, v172, v129
	v_pk_mul_f32 v[196:197], v[156:157], v[196:197]
	v_pk_mul_f32 v[198:199], v[158:159], v[198:199]
	v_pk_mul_f32 v[200:201], v[160:161], v[200:201]
	v_pk_mul_f32 v[202:203], v[162:163], v[202:203]
	v_pk_mul_f32 v[204:205], v[164:165], v[204:205]
	v_pk_mul_f32 v[206:207], v[166:167], v[206:207]
	v_pk_mul_f32 v[208:209], v[168:169], v[208:209]
	v_pk_mul_f32 v[210:211], v[170:171], v[210:211]
	ds_write_b128 v228, v[208:211]
	ds_write_b128 v228, v[204:207] offset:16
	ds_read_b128 v[232:235], v229
	ds_read_b128 v[236:239], v229 offset:1024
	s_waitcnt lgkmcnt(1)
	global_store_dwordx4 v230, v[232:235], s[34:35]
	s_waitcnt lgkmcnt(0)
	global_store_dwordx4 v231, v[236:239], s[34:35]
	ds_write_b128 v228, v[200:203]
	ds_write_b128 v228, v[196:199] offset:16
	ds_read_b128 v[240:243], v229
	ds_read_b128 v[244:247], v229 offset:1024
	s_waitcnt lgkmcnt(1)
	global_store_dwordx4 v230, v[240:243], s[34:35] offset:128
	s_waitcnt lgkmcnt(0)
	global_store_dwordx4 v231, v[244:247], s[34:35] offset:128
	s_add_u32 s34, s34, 0x10000
	s_addc_u32 s35, s35, 0
	v_mul_f32_e32 v212, v173, v98
	v_mul_f32_e32 v213, v173, v99
	v_mul_f32_e32 v214, v173, v100
	v_mul_f32_e32 v215, v173, v101
	v_mul_f32_e32 v216, v173, v102
	v_mul_f32_e32 v217, v173, v103
	v_mul_f32_e32 v218, v173, v104
	v_mul_f32_e32 v219, v173, v105
	v_mul_f32_e32 v220, v173, v106
	v_mul_f32_e32 v221, v173, v107
	v_mul_f32_e32 v222, v173, v108
	v_mul_f32_e32 v223, v173, v109
	v_mul_f32_e32 v224, v173, v110
	v_mul_f32_e32 v225, v173, v111
	v_mul_f32_e32 v226, v173, v112
	v_mul_f32_e32 v227, v173, v113
	v_pk_mul_f32 v[212:213], v[156:157], v[212:213]
	v_pk_mul_f32 v[214:215], v[158:159], v[214:215]
	v_pk_mul_f32 v[216:217], v[160:161], v[216:217]
	v_pk_mul_f32 v[218:219], v[162:163], v[218:219]
	v_pk_mul_f32 v[220:221], v[164:165], v[220:221]
	v_pk_mul_f32 v[222:223], v[166:167], v[222:223]
	v_pk_mul_f32 v[224:225], v[168:169], v[224:225]
	v_pk_mul_f32 v[226:227], v[170:171], v[226:227]
	ds_write_b128 v228, v[224:227]
	ds_write_b128 v228, v[220:223] offset:16
	ds_read_b128 v[240:243], v229
	ds_read_b128 v[244:247], v229 offset:1024
	s_waitcnt lgkmcnt(1)
	global_store_dwordx4 v230, v[240:243], s[34:35]
	s_waitcnt lgkmcnt(0)
	global_store_dwordx4 v231, v[244:247], s[34:35]
	ds_write_b128 v228, v[216:219]
	ds_write_b128 v228, v[212:215] offset:16
	ds_read_b128 v[240:243], v229
	ds_read_b128 v[244:247], v229 offset:1024
	s_waitcnt lgkmcnt(1)
	global_store_dwordx4 v230, v[240:243], s[34:35] offset:128
	s_waitcnt lgkmcnt(0)
; #define PG8_LAS __attribute__((address_space(3)))
; __device__ __forceinline__ void store_lines(PG8_LAS unsigned char* stg, const u32x4 P0, const u32x4 P1, int fr, int fq, bf16_t* seg0, int pitch) {
;     const int ln = fq * 16 + fr;
; #pragma unroll
;     for (int h = 0; h < 2; ++h) {
;         if ((fr >> 3) == h) { *(PG8_LAS u32x4*)(stg + (fr & 7) * 128 + fq * 16) = P0; *(PG8_LAS u32x4*)(stg + (fr & 7) * 128 + 64 + fq * 16) = P1; }
;         __builtin_amdgcn_wave_barrier(); asm volatile("" ::: "memory");
;         const u32x4 v = *(const PG8_LAS u32x4*)(stg + ln * 16);
;         __builtin_amdgcn_wave_barrier(); asm volatile("" ::: "memory");
;         *(u32x4*)(seg0 + (size_t)(8 * h + (ln >> 3)) * pitch + (ln & 7) * 8) = v; }
; __device__ __forceinline__ void p10_final(const Args& A, int lane, int wave, float* outp) {
;     ...
;     for (int m = gw; m < M; m += NGW) { const float rs = pg8::rstd_from(ssq, m);
; #pragma unroll
;         for (int j = 0; j < 2; ++j) { const int c = 8 * lane + 512 * j; f32x4 a, b; pg8::unpack8(*(const u32x4*)(X3 + (size_t)m * DM + c), a, b);
;             *(f32x4*)(outp + (size_t)m * DM + c) = (a * rs) * *(const f32x4*)(A.g_final + c); *(f32x4*)(outp + (size_t)m * DM + c + 4) = (b * rs) * *(const f32x4*)(A.g_final + c + 4); } }
	global_store_dwordx4 v231, v[244:247], s[34:35] offset:128
	s_add_u32 s34, s34, 0x10000
	s_addc_u32 s35, s35, 0
	v_mul_f32_e32 v196, v174, v82
	v_mul_f32_e32 v197, v174, v83
	v_mul_f32_e32 v198, v174, v84
	v_mul_f32_e32 v199, v174, v85
	v_mul_f32_e32 v200, v174, v86
	v_mul_f32_e32 v201, v174, v87
	v_mul_f32_e32 v202, v174, v88
	v_mul_f32_e32 v203, v174, v89
	v_mul_f32_e32 v204, v174, v90
	v_mul_f32_e32 v205, v174, v91
	v_mul_f32_e32 v206, v174, v92
	v_mul_f32_e32 v207, v174, v93
	v_mul_f32_e32 v208, v174, v94
	v_mul_f32_e32 v209, v174, v95
	v_mul_f32_e32 v210, v174, v96
	v_mul_f32_e32 v211, v174, v97
	v_pk_mul_f32 v[196:197], v[156:157], v[196:197]
	v_pk_mul_f32 v[198:199], v[158:159], v[198:199]
	v_pk_mul_f32 v[200:201], v[160:161], v[200:201]
	v_pk_mul_f32 v[202:203], v[162:163], v[202:203]
	v_pk_mul_f32 v[204:205], v[164:165], v[204:205]
	v_pk_mul_f32 v[206:207], v[166:167], v[206:207]
	v_pk_mul_f32 v[208:209], v[168:169], v[208:209]
	v_pk_mul_f32 v[210:211], v[170:171], v[210:211]
	ds_write_b128 v228, v[208:211]
	ds_write_b128 v228, v[204:207] offset:16
	ds_read_b128 v[232:235], v229
	ds_read_b128 v[236:239], v229 offset:1024
	s_waitcnt lgkmcnt(1)
	global_store_dwordx4 v230, v[232:235], s[34:35]
	s_waitcnt lgkmcnt(0)
	global_store_dwordx4 v231, v[236:239], s[34:35]
	ds_write_b128 v228, v[200:203]
	ds_write_b128 v228, v[196:199] offset:16
	ds_read_b128 v[240:243], v229
	ds_read_b128 v[244:247], v229 offset:1024
	s_waitcnt lgkmcnt(1)
	global_store_dwordx4 v230, v[240:243], s[34:35] offset:128
	s_waitcnt lgkmcnt(0)
	global_store_dwordx4 v231, v[244:247], s[34:35] offset:128
	s_add_u32 s34, s34, 0x10000
	s_addc_u32 s35, s35, 0
	v_mul_f32_e32 v212, v175, v66
	v_mul_f32_e32 v213, v175, v67
	v_mul_f32_e32 v214, v175, v68
	v_mul_f32_e32 v215, v175, v69
	v_mul_f32_e32 v216, v175, v70
	v_mul_f32_e32 v217, v175, v71
	v_mul_f32_e32 v218, v175, v72
	v_mul_f32_e32 v219, v175, v73
	v_mul_f32_e32 v220, v175, v74
	v_mul_f32_e32 v221, v175, v75
	v_mul_f32_e32 v222, v175, v76
	v_mul_f32_e32 v223, v175, v77
	v_mul_f32_e32 v224, v175, v78
	v_mul_f32_e32 v225, v175, v79
	v_mul_f32_e32 v226, v175, v80
	v_mul_f32_e32 v227, v175, v81
	v_pk_mul_f32 v[212:213], v[156:157], v[212:213]
	v_pk_mul_f32 v[214:215], v[158:159], v[214:215]
	v_pk_mul_f32 v[216:217], v[160:161], v[216:217]
	v_pk_mul_f32 v[218:219], v[162:163], v[218:219]
	v_pk_mul_f32 v[220:221], v[164:165], v[220:221]
	v_pk_mul_f32 v[222:223], v[166:167], v[222:223]
	v_pk_mul_f32 v[224:225], v[168:169], v[224:225]
	v_pk_mul_f32 v[226:227], v[170:171], v[226:227]
	ds_write_b128 v228, v[224:227]
	ds_write_b128 v228, v[220:223] offset:16
	ds_read_b128 v[240:243], v229
	ds_read_b128 v[244:247], v229 offset:1024
	s_waitcnt lgkmcnt(1)
	global_store_dwordx4 v230, v[240:243], s[34:35]
	s_waitcnt lgkmcnt(0)
	global_store_dwordx4 v231, v[244:247], s[34:35]
	ds_write_b128 v228, v[216:219]
	ds_write_b128 v228, v[212:215] offset:16
	ds_read_b128 v[240:243], v229
	ds_read_b128 v[244:247], v229 offset:1024
	s_waitcnt lgkmcnt(1)
	global_store_dwordx4 v230, v[240:243], s[34:35] offset:128
	s_waitcnt lgkmcnt(0)
	global_store_dwordx4 v231, v[244:247], s[34:35] offset:128
	s_add_u32 s34, s34, 0x50000
	s_addc_u32 s35, s35, 0
	v_mul_f32_e32 v196, v176, v50
	v_mul_f32_e32 v197, v176, v51
	v_mul_f32_e32 v198, v176, v52
	v_mul_f32_e32 v199, v176, v53
	v_mul_f32_e32 v200, v176, v54
	v_mul_f32_e32 v201, v176, v55
	v_mul_f32_e32 v202, v176, v56
	v_mul_f32_e32 v203, v176, v57
	v_mul_f32_e32 v204, v176, v58
	v_mul_f32_e32 v205, v176, v59
	v_mul_f32_e32 v206, v176, v60
	v_mul_f32_e32 v207, v176, v61
	v_mul_f32_e32 v208, v176, v62
	v_mul_f32_e32 v209, v176, v63
	v_mul_f32_e32 v210, v176, v64
	v_mul_f32_e32 v211, v176, v65
	v_pk_mul_f32 v[196:197], v[156:157], v[196:197]
	v_pk_mul_f32 v[198:199], v[158:159], v[198:199]
	v_pk_mul_f32 v[200:201], v[160:161], v[200:201]
	v_pk_mul_f32 v[202:203], v[162:163], v[202:203]
	v_pk_mul_f32 v[204:205], v[164:165], v[204:205]
	v_pk_mul_f32 v[206:207], v[166:167], v[206:207]
	v_pk_mul_f32 v[208:209], v[168:169], v[208:209]
	v_pk_mul_f32 v[210:211], v[170:171], v[210:211]
	ds_write_b128 v228, v[208:211]
	ds_write_b128 v228, v[204:207] offset:16
	ds_read_b128 v[232:235], v229
	ds_read_b128 v[236:239], v229 offset:1024
	s_waitcnt lgkmcnt(1)
	global_store_dwordx4 v230, v[232:235], s[34:35]
	s_waitcnt lgkmcnt(0)
	global_store_dwordx4 v231, v[236:239], s[34:35]
	ds_write_b128 v228, v[200:203]
	ds_write_b128 v228, v[196:199] offset:16
	ds_read_b128 v[240:243], v229
	ds_read_b128 v[244:247], v229 offset:1024
	s_waitcnt lgkmcnt(1)
	global_store_dwordx4 v230, v[240:243], s[34:35] offset:128
	s_waitcnt lgkmcnt(0)
; #define PG8_LAS __attribute__((address_space(3)))
; __device__ __forceinline__ void store_lines(PG8_LAS unsigned char* stg, const u32x4 P0, const u32x4 P1, int fr, int fq, bf16_t* seg0, int pitch) {
;     const int ln = fq * 16 + fr;
; #pragma unroll
;     for (int h = 0; h < 2; ++h) {
;         if ((fr >> 3) == h) { *(PG8_LAS u32x4*)(stg + (fr & 7) * 128 + fq * 16) = P0; *(PG8_LAS u32x4*)(stg + (fr & 7) * 128 + 64 + fq * 16) = P1; }
;         __builtin_amdgcn_wave_barrier(); asm volatile("" ::: "memory");
;         const u32x4 v = *(const PG8_LAS u32x4*)(stg + ln * 16);
;         __builtin_amdgcn_wave_barrier(); asm volatile("" ::: "memory");
;         *(u32x4*)(seg0 + (size_t)(8 * h + (ln >> 3)) * pitch + (ln & 7) * 8) = v; }
; __device__ __forceinline__ void p10_final(const Args& A, int lane, int wave, float* outp) {
;     ...
;     for (int m = gw; m < M; m += NGW) { const float rs = pg8::rstd_from(ssq, m);
; #pragma unroll
;         for (int j = 0; j < 2; ++j) { const int c = 8 * lane + 512 * j; f32x4 a, b; pg8::unpack8(*(const u32x4*)(X3 + (size_t)m * DM + c), a, b);
;             *(f32x4*)(outp + (size_t)m * DM + c) = (a * rs) * *(const f32x4*)(A.g_final + c); *(f32x4*)(outp + (size_t)m * DM + c + 4) = (b * rs) * *(const f32x4*)(A.g_final + c + 4); } }
	global_store_dwordx4 v231, v[244:247], s[34:35] offset:128
	s_add_u32 s34, s34, 0x10000
	s_addc_u32 s35, s35, 0
	v_mul_f32_e32 v212, v177, v34
	v_mul_f32_e32 v213, v177, v35
	v_mul_f32_e32 v214, v177, v36
	v_mul_f32_e32 v215, v177, v37
	v_mul_f32_e32 v216, v177, v38
	v_mul_f32_e32 v217, v177, v39
	v_mul_f32_e32 v218, v177, v40
	v_mul_f32_e32 v219, v177, v41
	v_mul_f32_e32 v220, v177, v42
	v_mul_f32_e32 v221, v177, v43
	v_mul_f32_e32 v222, v177, v44
	v_mul_f32_e32 v223, v177, v45
	v_mul_f32_e32 v224, v177, v46
	v_mul_f32_e32 v225, v177, v47
	v_mul_f32_e32 v226, v177, v48
	v_mul_f32_e32 v227, v177, v49
	v_pk_mul_f32 v[212:213], v[156:157], v[212:213]
	v_pk_mul_f32 v[214:215], v[158:159], v[214:215]
	v_pk_mul_f32 v[216:217], v[160:161], v[216:217]
	v_pk_mul_f32 v[218:219], v[162:163], v[218:219]
	v_pk_mul_f32 v[220:221], v[164:165], v[220:221]
	v_pk_mul_f32 v[222:223], v[166:167], v[222:223]
	v_pk_mul_f32 v[224:225], v[168:169], v[224:225]
	v_pk_mul_f32 v[226:227], v[170:171], v[226:227]
	ds_write_b128 v228, v[224:227]
	ds_write_b128 v228, v[220:223] offset:16
	ds_read_b128 v[240:243], v229
	ds_read_b128 v[244:247], v229 offset:1024
	s_waitcnt lgkmcnt(1)
	global_store_dwordx4 v230, v[240:243], s[34:35]
	s_waitcnt lgkmcnt(0)
	global_store_dwordx4 v231, v[244:247], s[34:35]
	ds_write_b128 v228, v[216:219]
	ds_write_b128 v228, v[212:215] offset:16
	ds_read_b128 v[240:243], v229
	ds_read_b128 v[244:247], v229 offset:1024
	s_waitcnt lgkmcnt(1)
	global_store_dwordx4 v230, v[240:243], s[34:35] offset:128
	s_waitcnt lgkmcnt(0)
	global_store_dwordx4 v231, v[244:247], s[34:35] offset:128
	s_add_u32 s34, s34, 0x10000
	s_addc_u32 s35, s35, 0
	v_mul_f32_e32 v196, v178, v18
	v_mul_f32_e32 v197, v178, v19
	v_mul_f32_e32 v198, v178, v20
	v_mul_f32_e32 v199, v178, v21
	v_mul_f32_e32 v200, v178, v22
	v_mul_f32_e32 v201, v178, v23
	v_mul_f32_e32 v202, v178, v24
	v_mul_f32_e32 v203, v178, v25
	v_mul_f32_e32 v204, v178, v26
	v_mul_f32_e32 v205, v178, v27
	v_mul_f32_e32 v206, v178, v28
	v_mul_f32_e32 v207, v178, v29
	v_mul_f32_e32 v208, v178, v30
	v_mul_f32_e32 v209, v178, v31
	v_mul_f32_e32 v210, v178, v32
	v_mul_f32_e32 v211, v178, v33
	v_pk_mul_f32 v[196:197], v[156:157], v[196:197]
	v_pk_mul_f32 v[198:199], v[158:159], v[198:199]
	v_pk_mul_f32 v[200:201], v[160:161], v[200:201]
	v_pk_mul_f32 v[202:203], v[162:163], v[202:203]
	v_pk_mul_f32 v[204:205], v[164:165], v[204:205]
	v_pk_mul_f32 v[206:207], v[166:167], v[206:207]
	v_pk_mul_f32 v[208:209], v[168:169], v[208:209]
	v_pk_mul_f32 v[210:211], v[170:171], v[210:211]
	ds_write_b128 v228, v[208:211]
	ds_write_b128 v228, v[204:207] offset:16
	ds_read_b128 v[232:235], v229
	ds_read_b128 v[236:239], v229 offset:1024
	s_waitcnt lgkmcnt(1)
	global_store_dwordx4 v230, v[232:235], s[34:35]
	s_waitcnt lgkmcnt(0)
	global_store_dwordx4 v231, v[236:239], s[34:35]
	ds_write_b128 v228, v[200:203]
	ds_write_b128 v228, v[196:199] offset:16
	ds_read_b128 v[240:243], v229
	ds_read_b128 v[244:247], v229 offset:1024
	s_waitcnt lgkmcnt(1)
	global_store_dwordx4 v230, v[240:243], s[34:35] offset:128
	s_waitcnt lgkmcnt(0)
	global_store_dwordx4 v231, v[244:247], s[34:35] offset:128
	s_add_u32 s34, s34, 0x10000
	s_addc_u32 s35, s35, 0
	v_mul_f32_e32 v212, v179, v2
	v_mul_f32_e32 v213, v179, v3
	v_mul_f32_e32 v214, v179, v4
	v_mul_f32_e32 v215, v179, v5
	v_mul_f32_e32 v216, v179, v6
	v_mul_f32_e32 v217, v179, v7
	v_mul_f32_e32 v218, v179, v8
	v_mul_f32_e32 v219, v179, v9
	v_mul_f32_e32 v220, v179, v10
	v_mul_f32_e32 v221, v179, v11
	v_mul_f32_e32 v222, v179, v12
	v_mul_f32_e32 v223, v179, v13
	v_mul_f32_e32 v224, v179, v14
	v_mul_f32_e32 v225, v179, v15
	v_mul_f32_e32 v226, v179, v16
	v_mul_f32_e32 v227, v179, v17
	v_pk_mul_f32 v[212:213], v[156:157], v[212:213]
	v_pk_mul_f32 v[214:215], v[158:159], v[214:215]
	v_pk_mul_f32 v[216:217], v[160:161], v[216:217]
	v_pk_mul_f32 v[218:219], v[162:163], v[218:219]
	v_pk_mul_f32 v[220:221], v[164:165], v[220:221]
	v_pk_mul_f32 v[222:223], v[166:167], v[222:223]
	v_pk_mul_f32 v[224:225], v[168:169], v[224:225]
	v_pk_mul_f32 v[226:227], v[170:171], v[226:227]
	ds_write_b128 v228, v[224:227]
	ds_write_b128 v228, v[220:223] offset:16
	ds_read_b128 v[240:243], v229
	ds_read_b128 v[244:247], v229 offset:1024
	s_waitcnt lgkmcnt(1)
	global_store_dwordx4 v230, v[240:243], s[34:35]
	s_waitcnt lgkmcnt(0)
	global_store_dwordx4 v231, v[244:247], s[34:35]
	ds_write_b128 v228, v[216:219]
	ds_write_b128 v228, v[212:215] offset:16
	ds_read_b128 v[240:243], v229
	ds_read_b128 v[244:247], v229 offset:1024
	s_waitcnt lgkmcnt(1)
	global_store_dwordx4 v230, v[240:243], s[34:35] offset:128
	s_waitcnt lgkmcnt(0)
	global_store_dwordx4 v231, v[244:247], s[34:35] offset:128
	s_and_b64 vcc, exec, s[2:3]
	s_mov_b64 s[0:1], -1
	s_cbranch_vccnz .LBB0_1057
	s_andn2_b64 vcc, exec, s[14:15]
	s_cbranch_vccnz .LBB0_1056
	s_barrier
	s_branch .LBB0_1056

; #define SEAM(k) do { if (IN(k) && IN((k) + 1)) xcd_barrier(bar); } while (0)
; __device__ __forceinline__ void xcd_barrier(const XcdBarrier& b) {
;     asm volatile("s_waitcnt vmcnt(0)" ::: "memory");
;     __syncthreads();
;     if (threadIdx.x == 0) {
;         unsigned* bar = b.bar;
;         __builtin_amdgcn_s_waitcnt(0);
;         unsigned nloc = b.st[0], nx = b.st[1];
;         if (nloc == 0u) { xcd_barrier_complete(bar, b.x, nloc, nx); b.st[0] = nloc; b.st[1] = nx; }
; __global__ void __launch_bounds__(512, 2) mk_fwd(Args A) {
;     ...
;         pg8::gemm_phase<pg8::EpiRes<true, false, true, true>, pg8::StaticOrder, true, true>(lds, g, S, E); } SEAM(9);
;     if (IN(10)) { int t10 = threadIdx.x; asm volatile("" : "+v"(t10)); p10_final(A, t10 & 63, wave, A.out); }
.LBB0_1124:
	s_endpgm
	s_cmp_gt_i32 s49, 10
	s_cselect_b64 s[0:1], -1, 0
	s_and_b64 s[2:3], s[8:9], s[0:1]
	s_andn2_b64 vcc, exec, s[2:3]
	s_cbranch_vccnz .LBB0_1174
	s_waitcnt vmcnt(0)
	v_cmp_eq_u32_e32 vcc, 0, v0
	s_waitcnt vmcnt(0) lgkmcnt(0)
	s_barrier
	s_and_saveexec_b64 s[2:3], vcc
	s_cbranch_execz .LBB0_1173
	v_mov_b32_e32 v1, s51
	s_waitcnt vmcnt(0) expcnt(0) lgkmcnt(0)
	ds_read_b32 v3, v1
	ds_read_b32 v1, v1 offset:4
	s_waitcnt lgkmcnt(1)
	v_cmp_ne_u32_e32 vcc, 0, v3
	s_cbranch_vccnz .LBB0_1141
	v_readlane_b32 s4, v254, 3
	v_readlane_b32 s5, v254, 4
	s_load_dwordx2 s[8:9], s[4:5], 0x4
	s_add_u32 s4, s78, 0x80200
	s_addc_u32 s5, s79, 0
	s_add_u32 s6, s78, 0x80400
	s_addc_u32 s7, s79, 0
	s_waitcnt lgkmcnt(0)
	s_mul_i32 s46, s8, s33
	s_add_u32 s8, s78, 0x80500
	s_mul_i32 s46, s46, s9
	s_addc_u32 s9, s79, 0
	s_add_u32 s10, s78, 0x80600
	s_addc_u32 s11, s79, 0
	s_add_u32 s12, s78, 0x80700
	s_addc_u32 s13, s79, 0
	s_add_u32 s14, s78, 0x80800
	s_addc_u32 s15, s79, 0
	s_add_u32 s16, s78, 0x80900
	s_addc_u32 s17, s79, 0
	s_add_u32 s18, s78, 0x80a00
	s_addc_u32 s19, s79, 0
	s_add_u32 s20, s78, 0x80b00
	s_addc_u32 s21, s79, 0
	s_add_u32 s22, s78, 0x80c00
	s_addc_u32 s23, s79, 0
	s_add_u32 s24, s78, 0x80d00
	s_addc_u32 s25, s79, 0
	s_add_u32 s26, s78, 0x80e00
	s_addc_u32 s27, s79, 0
	s_add_u32 s28, s78, 0x80f00
	s_addc_u32 s29, s79, 0
	s_add_u32 s30, s78, 0x81000
	s_addc_u32 s31, s79, 0
	s_add_u32 s34, s78, 0x81100
	s_addc_u32 s35, s79, 0
	s_add_u32 s36, s78, 0x81200
	s_addc_u32 s37, s79, 0
	s_add_u32 s38, s78, 0x81300
	s_addc_u32 s39, s79, 0
	s_mov_b32 s47, 1
	v_mov_b32_e32 v17, 0
	s_branch .LBB0_1129

; __global__ void __launch_bounds__(512, 2) mk_fwd(Args A) {
	.amdhsa_kernel _Z6mk_fwd4Args
		.amdhsa_group_segment_fixed_size 0
		.amdhsa_private_segment_fixed_size 0
		.amdhsa_kernarg_size 552
		.amdhsa_user_sgpr_count 2
		.amdhsa_user_sgpr_dispatch_ptr 0
		.amdhsa_user_sgpr_queue_ptr 0
		.amdhsa_user_sgpr_kernarg_segment_ptr 1
		.amdhsa_user_sgpr_dispatch_id 0
		.amdhsa_user_sgpr_kernarg_preload_length 0
		.amdhsa_user_sgpr_kernarg_preload_offset 0
		.amdhsa_user_sgpr_private_segment_size 0
		.amdhsa_uses_dynamic_stack 0
		.amdhsa_enable_private_segment 0
		.amdhsa_system_sgpr_workgroup_id_x 1
		.amdhsa_system_sgpr_workgroup_id_y 0
		.amdhsa_system_sgpr_workgroup_id_z 0
		.amdhsa_system_sgpr_workgroup_info 0
		.amdhsa_system_vgpr_workitem_id 0
		.amdhsa_next_free_vgpr 256
		.amdhsa_next_free_sgpr 102
		.amdhsa_accum_offset 256
		.amdhsa_reserve_vcc 1
		.amdhsa_float_round_mode_32 0
		.amdhsa_float_round_mode_16_64 0
		.amdhsa_float_denorm_mode_32 3
		.amdhsa_float_denorm_mode_16_64 3
		.amdhsa_dx10_clamp 1
		.amdhsa_ieee_mode 1
		.amdhsa_fp16_overflow 0
		.amdhsa_tg_split 0
		.amdhsa_exception_fp_ieee_invalid_op 0
		.amdhsa_exception_fp_denorm_src 0
		.amdhsa_exception_fp_ieee_div_zero 0
		.amdhsa_exception_fp_ieee_overflow 0
		.amdhsa_exception_fp_ieee_underflow 0
		.amdhsa_exception_fp_ieee_inexact 0
		.amdhsa_exception_int_div_zero 0
	.end_amdhsa_kernel

; __global__ void __launch_bounds__(512, 2) mk_fwd(Args A) {
amdhsa.kernels:
  - .agpr_count:     0
    .args:
      - .offset:         0
        .size:           296
        .value_kind:     by_value
      - .offset:         296
        .size:           4
        .value_kind:     hidden_block_count_x
      - .offset:         300
        .size:           4
        .value_kind:     hidden_block_count_y
      - .offset:         304
        .size:           4
        .value_kind:     hidden_block_count_z
      - .offset:         308
        .size:           2
        .value_kind:     hidden_group_size_x
      - .offset:         310
        .size:           2
        .value_kind:     hidden_group_size_y
      - .offset:         312
        .size:           2
        .value_kind:     hidden_group_size_z
      - .offset:         314
        .size:           2
        .value_kind:     hidden_remainder_x
      - .offset:         316
        .size:           2
        .value_kind:     hidden_remainder_y
      - .offset:         318
        .size:           2
        .value_kind:     hidden_remainder_z
      - .offset:         336
        .size:           8
        .value_kind:     hidden_global_offset_x
      - .offset:         344
        .size:           8
        .value_kind:     hidden_global_offset_y
      - .offset:         352
        .size:           8
        .value_kind:     hidden_global_offset_z
      - .offset:         360
        .size:           2
        .value_kind:     hidden_grid_dims
      - .offset:         416
        .size:           4
        .value_kind:     hidden_dynamic_lds_size
    .group_segment_fixed_size: 0
    .kernarg_segment_align: 8
    .kernarg_segment_size: 552
    .language:       OpenCL C
    .language_version:
      - 2
      - 0
    .max_flat_workgroup_size: 512
    .name:           _Z6mk_fwd4Args
    .private_segment_fixed_size: 0
    .sgpr_count:     108
    .sgpr_spill_count: 49
    .symbol:         _Z6mk_fwd4Args.kd
    .uniform_work_group_size: 1
    .uses_dynamic_stack: false
    .vgpr_count:     256
    .vgpr_spill_count: 0
    .wavefront_size: 64
